# P11 epilogue: LayerNorm stats staged in LDS (32 serialized global loads -> ds_read), on top of saddr DMA
# speedup vs baseline: 1.0069x; 1.0036x over previous
; #define PG8_STAGE(bufoff, gbase, voff) do { _Pragma("unroll") for (int _i = 0; _i < 2; ++_i) \
;         __builtin_amdgcn_global_load_lds((const unsigned*)((const char*)(gbase) + (voff)[_i]), (PG8_LAS unsigned*)(lds + (bufoff) + ldsw + _i * 8192), 16, 0, 0); } while (0)
; #define PG8_LDA(dst, b, h) do { _Pragma("unroll") for (int m = 0; m < 4; ++m) _Pragma("unroll") for (int k = 0; k < 2; ++k) dst[m][k] = *(const PG8_LAS bf16x8*)(lds + PG8_SA(b, h) + aoff + m * 2048 + k * 1024); } while (0)
; #define PG8_LDB(dst, b, h) do { _Pragma("unroll") for (int n = 0; n < 2; ++n) _Pragma("unroll") for (int k = 0; k < 2; ++k) dst[n][k] = *(const PG8_LAS bf16x8*)(lds + PG8_SB(b, h) + boff + n * 2048 + k * 1024); } while (0)
; #define PG8_MMA(ai, bj, At, Bt) do { __builtin_amdgcn_s_setprio(1); _Pragma("unroll") for (int m = 0; m < 4; ++m) _Pragma("unroll") for (int n = 0; n < 2; ++n) _Pragma("unroll") for (int k = 0; k < 2; ++k) \
;         acc[ai][bj][m][n] = __builtin_amdgcn_mfma_f32_16x16x32_bf16(Bt[n][k], At[m][k], acc[ai][bj][m][n], 0, 0, 0); __builtin_amdgcn_s_setprio(0); } while (0)
; #define PG8_WAIT_V(n) asm volatile("s_waitcnt vmcnt(" #n ")" ::: "memory")
; #define PG8_WAIT_L(n) asm volatile("s_waitcnt lgkmcnt(" #n ")" ::: "memory")
; #define PG8_BAR __builtin_amdgcn_s_barrier()
; #define PG8_SCHED __builtin_amdgcn_sched_barrier(0)
; template <class Epi, class Sched, bool ALIGN_EPI = false, bool SP2 = false>
; __device__ __forceinline__ void gemm_phase(PG8_LAS unsigned char* lds, const Gemm g, const Sched& S, const Epi& E) {
;     ...
;             PG8_LDB(B0, 0, 0); PG8_LDB(B1, 0, 1); PG8_SCHED; PG8_LDA(At, 0, 0); PG8_STAGE(PG8_SA(1, 1), a1 + hstepA, voffA);
;             PG8_WAIT_V(8); PG8_WAIT_L(0); PG8_BAR; PG8_MMA(0, 0, At, B0); PG8_MMA(0, 1, At, B1); PG8_BAR; PG8_SCHED;
;     ...
; #pragma unroll
;         for (int a = 0; a < 2; ++a)
; #pragma unroll
;             for (int b = 0; b < 2; ++b)
; #pragma unroll
;                 for (int m = 0; m < 4; ++m)
; #pragma unroll
;                     for (int n = 0; n < 2; ++n) acc[a][b][m][n] = (f32x4){0.f, 0.f, 0.f, 0.f};
;         cur = nxt; cA = nA; cB = nB; ++ui;
.LBB0_1126:
	s_ashr_i32 s25, s24, 31
	s_lshl_b64 s[26:27], s[24:25], 21
	s_add_u32 s36, s54, s26
	s_addc_u32 s37, s55, s27
	s_and_b64 s[26:27], s[4:5], exec
	s_cselect_b32 s25, s37, s41
	s_cselect_b32 s26, s36, s40
	s_ashr_i32 s23, s22, 31
	s_lshl_b64 s[34:35], s[22:23], 21
	s_add_u32 s38, s19, s34
	s_addc_u32 s39, s21, s35
	s_and_b64 s[34:35], s[4:5], exec
	s_cselect_b32 s23, s39, s43
	s_cselect_b32 s27, s38, s42
	s_add_u32 s40, s40, 0x100080
	s_addc_u32 s41, s41, 0
	s_add_u32 s45, s42, 0x100
	v_mov_b32_e32 v2, 0
	s_addc_u32 s52, s43, 0
	s_mov_b32 s53, -2
	v_mov_b32_e32 v3, v2
	v_mov_b32_e32 v4, v2
	v_mov_b32_e32 v5, v2
	v_mov_b32_e32 v14, v2
	v_mov_b32_e32 v15, v2
	v_mov_b32_e32 v16, v2
	v_mov_b32_e32 v17, v2
	v_mov_b32_e32 v18, v2
	v_mov_b32_e32 v19, v2
	v_mov_b32_e32 v20, v2
	v_mov_b32_e32 v21, v2
	v_mov_b32_e32 v30, v2
	v_mov_b32_e32 v31, v2
	v_mov_b32_e32 v32, v2
	v_mov_b32_e32 v33, v2
	v_mov_b32_e32 v34, v2
	v_mov_b32_e32 v35, v2
	v_mov_b32_e32 v36, v2
	v_mov_b32_e32 v37, v2
	v_mov_b32_e32 v46, v2
	v_mov_b32_e32 v47, v2
	v_mov_b32_e32 v48, v2
	v_mov_b32_e32 v49, v2
	v_mov_b32_e32 v50, v2
	v_mov_b32_e32 v51, v2
	v_mov_b32_e32 v52, v2
	v_mov_b32_e32 v53, v2
	v_mov_b32_e32 v62, v2
	v_mov_b32_e32 v63, v2
	v_mov_b32_e32 v64, v2
	v_mov_b32_e32 v65, v2
	v_mov_b32_e32 v6, v2
	v_mov_b32_e32 v7, v2
	v_mov_b32_e32 v8, v2
	v_mov_b32_e32 v9, v2
	v_mov_b32_e32 v10, v2
	v_mov_b32_e32 v11, v2
	v_mov_b32_e32 v12, v2
	v_mov_b32_e32 v13, v2
	v_mov_b32_e32 v22, v2
	v_mov_b32_e32 v23, v2
	v_mov_b32_e32 v24, v2
	v_mov_b32_e32 v25, v2
	v_mov_b32_e32 v26, v2
	v_mov_b32_e32 v27, v2
	v_mov_b32_e32 v28, v2
	v_mov_b32_e32 v29, v2
	v_mov_b32_e32 v38, v2
	v_mov_b32_e32 v39, v2
	v_mov_b32_e32 v40, v2
	v_mov_b32_e32 v41, v2
	v_mov_b32_e32 v42, v2
	v_mov_b32_e32 v43, v2
	v_mov_b32_e32 v44, v2
	v_mov_b32_e32 v45, v2
	v_mov_b32_e32 v54, v2
	v_mov_b32_e32 v55, v2
	v_mov_b32_e32 v56, v2
	v_mov_b32_e32 v57, v2
	v_mov_b32_e32 v58, v2
	v_mov_b32_e32 v59, v2
	v_mov_b32_e32 v60, v2
	v_mov_b32_e32 v61, v2
	v_mov_b32_e32 v66, v2
	v_mov_b32_e32 v67, v2
	v_mov_b32_e32 v68, v2
	v_mov_b32_e32 v69, v2
	v_mov_b32_e32 v78, v2
	v_mov_b32_e32 v79, v2
	v_mov_b32_e32 v80, v2
	v_mov_b32_e32 v81, v2
	v_mov_b32_e32 v82, v2
	v_mov_b32_e32 v83, v2
	v_mov_b32_e32 v84, v2
	v_mov_b32_e32 v85, v2
	v_mov_b32_e32 v94, v2
	v_mov_b32_e32 v95, v2
	v_mov_b32_e32 v96, v2
	v_mov_b32_e32 v97, v2
	v_mov_b32_e32 v98, v2
	v_mov_b32_e32 v99, v2
	v_mov_b32_e32 v100, v2
	v_mov_b32_e32 v101, v2
	v_mov_b32_e32 v110, v2
	v_mov_b32_e32 v111, v2
	v_mov_b32_e32 v112, v2
	v_mov_b32_e32 v113, v2
	v_mov_b32_e32 v114, v2
	v_mov_b32_e32 v115, v2
	v_mov_b32_e32 v116, v2
	v_mov_b32_e32 v117, v2
	v_mov_b32_e32 v126, v2
	v_mov_b32_e32 v127, v2
	v_mov_b32_e32 v128, v2
	v_mov_b32_e32 v129, v2
	v_mov_b32_e32 v70, v2
	v_mov_b32_e32 v71, v2
	v_mov_b32_e32 v72, v2
	v_mov_b32_e32 v73, v2
	v_mov_b32_e32 v74, v2
	v_mov_b32_e32 v75, v2
	v_mov_b32_e32 v76, v2
	v_mov_b32_e32 v77, v2
	v_mov_b32_e32 v86, v2
	v_mov_b32_e32 v87, v2
	v_mov_b32_e32 v88, v2
	v_mov_b32_e32 v89, v2
	v_mov_b32_e32 v90, v2
	v_mov_b32_e32 v91, v2
	v_mov_b32_e32 v92, v2
	v_mov_b32_e32 v93, v2
	v_mov_b32_e32 v102, v2
	v_mov_b32_e32 v103, v2
	v_mov_b32_e32 v104, v2
	v_mov_b32_e32 v105, v2
	v_mov_b32_e32 v106, v2
	v_mov_b32_e32 v107, v2
	v_mov_b32_e32 v108, v2
	v_mov_b32_e32 v109, v2
	v_mov_b32_e32 v118, v2
	v_mov_b32_e32 v119, v2
	v_mov_b32_e32 v120, v2
	v_mov_b32_e32 v121, v2
	v_mov_b32_e32 v122, v2
	v_mov_b32_e32 v123, v2
	v_mov_b32_e32 v124, v2
	v_mov_b32_e32 v125, v2
	v_readfirstlane_b32 s98, v0
	s_nop 1
	s_cmpk_gt_u32 s98, 0x7f
	s_cbranch_scc1 .Lp11_st_skip
	s_lshl_b32 s98, s6, 11
	s_add_u32 s100, s8, s98
	s_addc_u32 s101, s9, 0
	v_lshlrev_b32_e32 v232, 4, v0
	global_load_dwordx4 v[228:231], v232, s[100:101]
.Lp11_st_skip:
.LBB0_1127:
	ds_read_b128 v[130:133], v203
	ds_read_b128 v[134:137], v203 offset:1024
	ds_read_b128 v[138:141], v203 offset:2048
	ds_read_b128 v[142:145], v203 offset:3072
	ds_read_b128 v[146:149], v205
	ds_read_b128 v[150:153], v205 offset:1024
	ds_read_b128 v[154:157], v205 offset:2048
	ds_read_b128 v[158:161], v205 offset:3072
	s_add_u32 s34, s40, 0xfff00080
	s_addc_u32 s35, s41, -1
	s_cmp_eq_u32 s53, 60
	s_cselect_b32 s35, s25, s35
	s_cselect_b32 s34, s26, s34
	s_cselect_b32 s43, s23, s52
	s_cselect_b32 s42, s27, s45
	s_add_i32 m0, s47, 0xc000
	ds_read_b128 v[162:165], v207
	ds_read_b128 v[166:169], v207 offset:1024
	ds_read_b128 v[170:173], v207 offset:2048
	ds_read_b128 v[174:177], v207 offset:3072
	ds_read_b128 v[196:199], v207 offset:4096
	ds_read_b128 v[208:211], v207 offset:5120
	ds_read_b128 v[212:215], v207 offset:6144
	ds_read_b128 v[216:219], v207 offset:7168
	global_load_lds_dwordx4 v188, s[40:41]
	s_add_i32 m0, s47, 0xe000
	s_nop 0
	global_load_lds_dwordx4 v190, s[40:41]
	s_waitcnt vmcnt(8)
	s_waitcnt lgkmcnt(0)
	s_barrier
; #define PG8_STAGE(bufoff, gbase, voff) do { _Pragma("unroll") for (int _i = 0; _i < 2; ++_i) \
;         __builtin_amdgcn_global_load_lds((const unsigned*)((const char*)(gbase) + (voff)[_i]), (PG8_LAS unsigned*)(lds + (bufoff) + ldsw + _i * 8192), 16, 0, 0); } while (0)
; #define PG8_LDA(dst, b, h) do { _Pragma("unroll") for (int m = 0; m < 4; ++m) _Pragma("unroll") for (int k = 0; k < 2; ++k) dst[m][k] = *(const PG8_LAS bf16x8*)(lds + PG8_SA(b, h) + aoff + m * 2048 + k * 1024); } while (0)
; #define PG8_MMA(ai, bj, At, Bt) do { __builtin_amdgcn_s_setprio(1); _Pragma("unroll") for (int m = 0; m < 4; ++m) _Pragma("unroll") for (int n = 0; n < 2; ++n) _Pragma("unroll") for (int k = 0; k < 2; ++k) \
;         acc[ai][bj][m][n] = __builtin_amdgcn_mfma_f32_16x16x32_bf16(Bt[n][k], At[m][k], acc[ai][bj][m][n], 0, 0, 0); __builtin_amdgcn_s_setprio(0); } while (0)
; #define PG8_WAIT_V(n) asm volatile("s_waitcnt vmcnt(" #n ")" ::: "memory")
; #define PG8_WAIT_L(n) asm volatile("s_waitcnt lgkmcnt(" #n ")" ::: "memory")
; #define PG8_BAR __builtin_amdgcn_s_barrier()
; #define PG8_SCHED __builtin_amdgcn_sched_barrier(0)
; template <class Epi, class Sched, bool ALIGN_EPI = false, bool SP2 = false>
; __device__ __forceinline__ void gemm_phase(PG8_LAS unsigned char* lds, const Gemm g, const Sched& S, const Epi& E) {
;     ...
;             PG8_WAIT_V(8); PG8_WAIT_L(0); PG8_BAR; PG8_MMA(0, 0, At, B0); PG8_MMA(0, 1, At, B1); PG8_BAR; PG8_SCHED;
;             PG8_LDA(At, 0, 1); PG8_STAGE(PG8_SB(0, 0), b2, voffB); PG8_STAGE(PG8_SB(0, 1), b2 + hstepB, voffB); PG8_STAGE(PG8_SA(0, 0), a2, voffA);
;             PG8_WAIT_V(8); PG8_WAIT_L(0); PG8_BAR; PG8_MMA(1, 0, At, B0); PG8_MMA(1, 1, At, B1); PG8_BAR; PG8_SCHED;
	s_setprio 1
	s_waitcnt lgkmcnt(0)
	v_mfma_f32_16x16x32_bf16 v[122:125], v[130:133], v[162:165], v[122:125]
	v_mfma_f32_16x16x32_bf16 v[118:121], v[138:141], v[162:165], v[118:121]
	v_mfma_f32_16x16x32_bf16 v[106:109], v[130:133], v[170:173], v[106:109]
	v_mfma_f32_16x16x32_bf16 v[102:105], v[138:141], v[170:173], v[102:105]
	v_mfma_f32_16x16x32_bf16 v[90:93], v[130:133], v[196:199], v[90:93]
	v_mfma_f32_16x16x32_bf16 v[86:89], v[138:141], v[196:199], v[86:89]
	v_mfma_f32_16x16x32_bf16 v[74:77], v[130:133], v[212:215], v[74:77]
	v_mfma_f32_16x16x32_bf16 v[70:73], v[138:141], v[212:215], v[70:73]
	v_mfma_f32_16x16x32_bf16 v[122:125], v[134:137], v[166:169], v[122:125]
	v_mfma_f32_16x16x32_bf16 v[118:121], v[142:145], v[166:169], v[118:121]
	v_mfma_f32_16x16x32_bf16 v[106:109], v[134:137], v[174:177], v[106:109]
	v_mfma_f32_16x16x32_bf16 v[102:105], v[142:145], v[174:177], v[102:105]
	v_mfma_f32_16x16x32_bf16 v[90:93], v[134:137], v[208:211], v[90:93]
	v_mfma_f32_16x16x32_bf16 v[86:89], v[142:145], v[208:211], v[86:89]
	v_mfma_f32_16x16x32_bf16 v[74:77], v[134:137], v[216:219], v[74:77]
	v_mfma_f32_16x16x32_bf16 v[70:73], v[142:145], v[216:219], v[70:73]
	s_setprio 0
	s_setprio 1
	v_mfma_f32_16x16x32_bf16 v[126:129], v[146:149], v[162:165], v[126:129]
	v_mfma_f32_16x16x32_bf16 v[114:117], v[154:157], v[162:165], v[114:117]
	v_mfma_f32_16x16x32_bf16 v[110:113], v[146:149], v[170:173], v[110:113]
	v_mfma_f32_16x16x32_bf16 v[98:101], v[154:157], v[170:173], v[98:101]
	v_mfma_f32_16x16x32_bf16 v[94:97], v[146:149], v[196:199], v[94:97]
	v_mfma_f32_16x16x32_bf16 v[82:85], v[154:157], v[196:199], v[82:85]
	v_mfma_f32_16x16x32_bf16 v[78:81], v[146:149], v[212:215], v[78:81]
	v_mfma_f32_16x16x32_bf16 v[66:69], v[154:157], v[212:215], v[66:69]
	v_mfma_f32_16x16x32_bf16 v[126:129], v[150:153], v[166:169], v[126:129]
	v_mfma_f32_16x16x32_bf16 v[114:117], v[158:161], v[166:169], v[114:117]
	v_mfma_f32_16x16x32_bf16 v[110:113], v[150:153], v[174:177], v[110:113]
	v_mfma_f32_16x16x32_bf16 v[98:101], v[158:161], v[174:177], v[98:101]
	v_mfma_f32_16x16x32_bf16 v[94:97], v[150:153], v[208:211], v[94:97]
	v_mfma_f32_16x16x32_bf16 v[82:85], v[158:161], v[208:211], v[82:85]
	v_mfma_f32_16x16x32_bf16 v[78:81], v[150:153], v[216:219], v[78:81]
	v_mfma_f32_16x16x32_bf16 v[66:69], v[158:161], v[216:219], v[66:69]
	s_setprio 0
	s_barrier
	s_add_i32 s73, s68, s17
	s_add_u32 s98, s42, 0x80
	s_addc_u32 s99, s43, 0
	s_add_u32 s100, s34, 0x80
	s_addc_u32 s101, s35, 0
	s_mov_b32 m0, s73
	ds_read_b128 v[162:165], v207 offset:16384
	ds_read_b128 v[166:169], v207 offset:17408
	ds_read_b128 v[170:173], v207 offset:18432
	ds_read_b128 v[174:177], v207 offset:19456
	ds_read_b128 v[196:199], v207 offset:20480
	ds_read_b128 v[208:211], v207 offset:21504
	ds_read_b128 v[212:215], v207 offset:22528
	ds_read_b128 v[216:219], v207 offset:23552
	global_load_lds_dwordx4 v182, s[42:43]
	s_add_i32 m0, s73, 0x2000
	s_add_u32 s74, s42, 0x100000
	s_addc_u32 s75, s43, 0
	s_add_i32 s73, s69, s17
	global_load_lds_dwordx4 v178, s[42:43]
	s_mov_b32 m0, s73
	s_nop 0
	global_load_lds_dwordx4 v182, s[74:75]
	s_add_i32 m0, s73, 0x2000
	s_nop 0
	global_load_lds_dwordx4 v178, s[74:75]
	s_mov_b32 m0, s47
	s_nop 0
	global_load_lds_dwordx4 v184, s[34:35]
	s_mov_b32 m0, s48
	s_nop 0
	global_load_lds_dwordx4 v180, s[34:35]
	s_waitcnt vmcnt(8)
	s_waitcnt lgkmcnt(0)
	s_barrier
	s_setprio 1
	s_waitcnt lgkmcnt(0)
	v_mfma_f32_16x16x32_bf16 v[58:61], v[130:133], v[162:165], v[58:61]
	v_mfma_f32_16x16x32_bf16 v[54:57], v[138:141], v[162:165], v[54:57]
	v_mfma_f32_16x16x32_bf16 v[42:45], v[130:133], v[170:173], v[42:45]
	v_mfma_f32_16x16x32_bf16 v[38:41], v[138:141], v[170:173], v[38:41]
	v_mfma_f32_16x16x32_bf16 v[26:29], v[130:133], v[196:199], v[26:29]
	v_mfma_f32_16x16x32_bf16 v[22:25], v[138:141], v[196:199], v[22:25]
	v_mfma_f32_16x16x32_bf16 v[10:13], v[130:133], v[212:215], v[10:13]
	v_mfma_f32_16x16x32_bf16 v[6:9], v[138:141], v[212:215], v[6:9]
	v_mfma_f32_16x16x32_bf16 v[58:61], v[134:137], v[166:169], v[58:61]
	v_mfma_f32_16x16x32_bf16 v[54:57], v[142:145], v[166:169], v[54:57]
	v_mfma_f32_16x16x32_bf16 v[42:45], v[134:137], v[174:177], v[42:45]
	v_mfma_f32_16x16x32_bf16 v[38:41], v[142:145], v[174:177], v[38:41]
	v_mfma_f32_16x16x32_bf16 v[26:29], v[134:137], v[208:211], v[26:29]
	v_mfma_f32_16x16x32_bf16 v[22:25], v[142:145], v[208:211], v[22:25]
	v_mfma_f32_16x16x32_bf16 v[10:13], v[134:137], v[216:219], v[10:13]
	v_mfma_f32_16x16x32_bf16 v[6:9], v[142:145], v[216:219], v[6:9]
	s_setprio 0
	s_setprio 1
	v_mfma_f32_16x16x32_bf16 v[62:65], v[146:149], v[162:165], v[62:65]
	v_mfma_f32_16x16x32_bf16 v[50:53], v[154:157], v[162:165], v[50:53]
	v_mfma_f32_16x16x32_bf16 v[46:49], v[146:149], v[170:173], v[46:49]
	v_mfma_f32_16x16x32_bf16 v[34:37], v[154:157], v[170:173], v[34:37]
	v_mfma_f32_16x16x32_bf16 v[30:33], v[146:149], v[196:199], v[30:33]
	v_mfma_f32_16x16x32_bf16 v[18:21], v[154:157], v[196:199], v[18:21]
	v_mfma_f32_16x16x32_bf16 v[14:17], v[146:149], v[212:215], v[14:17]
	v_mfma_f32_16x16x32_bf16 v[2:5], v[154:157], v[212:215], v[2:5]
	v_mfma_f32_16x16x32_bf16 v[62:65], v[150:153], v[166:169], v[62:65]
	v_mfma_f32_16x16x32_bf16 v[50:53], v[158:161], v[166:169], v[50:53]
	v_mfma_f32_16x16x32_bf16 v[46:49], v[150:153], v[174:177], v[46:49]
	v_mfma_f32_16x16x32_bf16 v[34:37], v[158:161], v[174:177], v[34:37]
	v_mfma_f32_16x16x32_bf16 v[30:33], v[150:153], v[208:211], v[30:33]
	v_mfma_f32_16x16x32_bf16 v[18:21], v[158:161], v[208:211], v[18:21]
	v_mfma_f32_16x16x32_bf16 v[14:17], v[150:153], v[216:219], v[14:17]
	v_mfma_f32_16x16x32_bf16 v[2:5], v[158:161], v[216:219], v[2:5]
	s_setprio 0
	s_barrier
; #define PG8_STAGE(bufoff, gbase, voff) do { _Pragma("unroll") for (int _i = 0; _i < 2; ++_i) \
;         __builtin_amdgcn_global_load_lds((const unsigned*)((const char*)(gbase) + (voff)[_i]), (PG8_LAS unsigned*)(lds + (bufoff) + ldsw + _i * 8192), 16, 0, 0); } while (0)
; #define PG8_LDA(dst, b, h) do { _Pragma("unroll") for (int m = 0; m < 4; ++m) _Pragma("unroll") for (int k = 0; k < 2; ++k) dst[m][k] = *(const PG8_LAS bf16x8*)(lds + PG8_SA(b, h) + aoff + m * 2048 + k * 1024); } while (0)
; #define PG8_LDB(dst, b, h) do { _Pragma("unroll") for (int n = 0; n < 2; ++n) _Pragma("unroll") for (int k = 0; k < 2; ++k) dst[n][k] = *(const PG8_LAS bf16x8*)(lds + PG8_SB(b, h) + boff + n * 2048 + k * 1024); } while (0)
; #define PG8_MMA(ai, bj, At, Bt) do { __builtin_amdgcn_s_setprio(1); _Pragma("unroll") for (int m = 0; m < 4; ++m) _Pragma("unroll") for (int n = 0; n < 2; ++n) _Pragma("unroll") for (int k = 0; k < 2; ++k) \
;         acc[ai][bj][m][n] = __builtin_amdgcn_mfma_f32_16x16x32_bf16(Bt[n][k], At[m][k], acc[ai][bj][m][n], 0, 0, 0); __builtin_amdgcn_s_setprio(0); } while (0)
; #define PG8_WAIT_V(n) asm volatile("s_waitcnt vmcnt(" #n ")" ::: "memory")
; #define PG8_WAIT_L(n) asm volatile("s_waitcnt lgkmcnt(" #n ")" ::: "memory")
; #define PG8_BAR __builtin_amdgcn_s_barrier()
; #define PG8_SCHED __builtin_amdgcn_sched_barrier(0)
; template <class Epi, class Sched, bool ALIGN_EPI = false, bool SP2 = false>
; __device__ __forceinline__ void gemm_phase(PG8_LAS unsigned char* lds, const Gemm g, const Sched& S, const Epi& E) {
;     ...
;             PG8_LDB(B0, 1, 0); PG8_LDB(B1, 1, 1); PG8_SCHED; PG8_LDA(At, 1, 0); PG8_STAGE(PG8_SA(0, 1), a2 + hstepA, voffA);
;             PG8_WAIT_V(8); PG8_WAIT_L(0); PG8_BAR; PG8_MMA(0, 0, At, B0); PG8_MMA(0, 1, At, B1); PG8_BAR; PG8_SCHED;
;             PG8_LDA(At, 1, 1); PG8_STAGE(PG8_SB(1, 0), b3, voffB); PG8_STAGE(PG8_SB(1, 1), b3 + hstepB, voffB); PG8_STAGE(PG8_SA(1, 0), a3, voffA);
;             PG8_WAIT_V(8); PG8_WAIT_L(0); PG8_BAR; PG8_MMA(1, 0, At, B0); PG8_MMA(1, 1, At, B1); PG8_BAR; PG8_SCHED;
	s_add_i32 s73, 0, 0x18000
	s_add_i32 s74, 0, 0x1c000
	v_add_u32_e32 v142, s73, v1
	v_add_u32_e32 v158, s74, v1
	ds_read_b128 v[130:133], v142
	ds_read_b128 v[134:137], v142 offset:1024
	ds_read_b128 v[138:141], v142 offset:2048
	ds_read_b128 v[142:145], v142 offset:3072
	ds_read_b128 v[146:149], v158
	ds_read_b128 v[150:153], v158 offset:1024
	ds_read_b128 v[154:157], v158 offset:2048
	ds_read_b128 v[158:161], v158 offset:3072
	s_add_u32 s34, s34, 0x100000
	s_addc_u32 s35, s35, 0
	s_mov_b32 m0, s49
	ds_read_b128 v[162:165], v207 offset:32768
	ds_read_b128 v[166:169], v207 offset:33792
	ds_read_b128 v[170:173], v207 offset:34816
	ds_read_b128 v[174:177], v207 offset:35840
	ds_read_b128 v[196:199], v207 offset:36864
	ds_read_b128 v[208:211], v207 offset:37888
	ds_read_b128 v[212:215], v207 offset:38912
	ds_read_b128 v[216:219], v207 offset:39936
	global_load_lds_dwordx4 v184, s[34:35]
	s_mov_b32 m0, s60
	s_nop 0
	global_load_lds_dwordx4 v180, s[34:35]
	s_waitcnt vmcnt(8)
	s_waitcnt lgkmcnt(0)
	s_barrier
	s_setprio 1
	s_waitcnt lgkmcnt(0)
	v_mfma_f32_16x16x32_bf16 v[122:125], v[130:133], v[162:165], v[122:125]
	v_mfma_f32_16x16x32_bf16 v[118:121], v[138:141], v[162:165], v[118:121]
	v_mfma_f32_16x16x32_bf16 v[106:109], v[130:133], v[170:173], v[106:109]
	v_mfma_f32_16x16x32_bf16 v[102:105], v[138:141], v[170:173], v[102:105]
	v_mfma_f32_16x16x32_bf16 v[90:93], v[130:133], v[196:199], v[90:93]
	v_mfma_f32_16x16x32_bf16 v[86:89], v[138:141], v[196:199], v[86:89]
	v_mfma_f32_16x16x32_bf16 v[74:77], v[130:133], v[212:215], v[74:77]
	v_mfma_f32_16x16x32_bf16 v[70:73], v[138:141], v[212:215], v[70:73]
	v_mfma_f32_16x16x32_bf16 v[122:125], v[134:137], v[166:169], v[122:125]
	v_mfma_f32_16x16x32_bf16 v[118:121], v[142:145], v[166:169], v[118:121]
	v_mfma_f32_16x16x32_bf16 v[106:109], v[134:137], v[174:177], v[106:109]
	v_mfma_f32_16x16x32_bf16 v[102:105], v[142:145], v[174:177], v[102:105]
	v_mfma_f32_16x16x32_bf16 v[90:93], v[134:137], v[208:211], v[90:93]
	v_mfma_f32_16x16x32_bf16 v[86:89], v[142:145], v[208:211], v[86:89]
	v_mfma_f32_16x16x32_bf16 v[74:77], v[134:137], v[216:219], v[74:77]
	v_mfma_f32_16x16x32_bf16 v[70:73], v[142:145], v[216:219], v[70:73]
	s_setprio 0
	s_setprio 1
	v_mfma_f32_16x16x32_bf16 v[126:129], v[146:149], v[162:165], v[126:129]
	v_mfma_f32_16x16x32_bf16 v[114:117], v[154:157], v[162:165], v[114:117]
	v_mfma_f32_16x16x32_bf16 v[110:113], v[146:149], v[170:173], v[110:113]
	v_mfma_f32_16x16x32_bf16 v[98:101], v[154:157], v[170:173], v[98:101]
	v_mfma_f32_16x16x32_bf16 v[94:97], v[146:149], v[196:199], v[94:97]
	v_mfma_f32_16x16x32_bf16 v[82:85], v[154:157], v[196:199], v[82:85]
	v_mfma_f32_16x16x32_bf16 v[78:81], v[146:149], v[212:215], v[78:81]
	v_mfma_f32_16x16x32_bf16 v[66:69], v[154:157], v[212:215], v[66:69]
	v_mfma_f32_16x16x32_bf16 v[126:129], v[150:153], v[166:169], v[126:129]
	v_mfma_f32_16x16x32_bf16 v[114:117], v[158:161], v[166:169], v[114:117]
	v_mfma_f32_16x16x32_bf16 v[110:113], v[150:153], v[174:177], v[110:113]
	v_mfma_f32_16x16x32_bf16 v[98:101], v[158:161], v[174:177], v[98:101]
	v_mfma_f32_16x16x32_bf16 v[94:97], v[150:153], v[208:211], v[94:97]
	v_mfma_f32_16x16x32_bf16 v[82:85], v[158:161], v[208:211], v[82:85]
	v_mfma_f32_16x16x32_bf16 v[78:81], v[150:153], v[216:219], v[78:81]
	v_mfma_f32_16x16x32_bf16 v[66:69], v[158:161], v[216:219], v[66:69]
	s_setprio 0
	s_barrier
	s_add_i32 s34, s73, s17
	s_mov_b32 m0, s34
	ds_read_b128 v[162:165], v207 offset:49152
	ds_read_b128 v[166:169], v207 offset:50176
	ds_read_b128 v[170:173], v207 offset:51200
	ds_read_b128 v[174:177], v207 offset:52224
	ds_read_b128 v[196:199], v207 offset:53248
	ds_read_b128 v[208:211], v207 offset:54272
	ds_read_b128 v[212:215], v207 offset:55296
	ds_read_b128 v[216:219], v207 offset:56320
	global_load_lds_dwordx4 v182, s[98:99]
	s_add_i32 m0, s34, 0x2000
	s_add_u32 s34, s42, 0x100080
	s_addc_u32 s35, s43, 0
	s_add_i32 s42, s74, s17
	global_load_lds_dwordx4 v178, s[98:99]
	s_mov_b32 m0, s42
	s_nop 0
	global_load_lds_dwordx4 v182, s[34:35]
	s_add_i32 m0, s42, 0x2000
	s_nop 0
	global_load_lds_dwordx4 v178, s[34:35]
	s_mov_b32 m0, s64
	s_nop 0
	global_load_lds_dwordx4 v184, s[100:101]
	s_mov_b32 m0, s65
	s_nop 0
	global_load_lds_dwordx4 v180, s[100:101]
	s_waitcnt vmcnt(8)
	s_waitcnt lgkmcnt(0)
	s_barrier
	s_setprio 1
	s_waitcnt lgkmcnt(0)
	v_mfma_f32_16x16x32_bf16 v[58:61], v[130:133], v[162:165], v[58:61]
	v_mfma_f32_16x16x32_bf16 v[54:57], v[138:141], v[162:165], v[54:57]
	v_mfma_f32_16x16x32_bf16 v[42:45], v[130:133], v[170:173], v[42:45]
	v_mfma_f32_16x16x32_bf16 v[38:41], v[138:141], v[170:173], v[38:41]
	v_mfma_f32_16x16x32_bf16 v[26:29], v[130:133], v[196:199], v[26:29]
	v_mfma_f32_16x16x32_bf16 v[22:25], v[138:141], v[196:199], v[22:25]
	v_mfma_f32_16x16x32_bf16 v[10:13], v[130:133], v[212:215], v[10:13]
	v_mfma_f32_16x16x32_bf16 v[6:9], v[138:141], v[212:215], v[6:9]
	v_mfma_f32_16x16x32_bf16 v[58:61], v[134:137], v[166:169], v[58:61]
	v_mfma_f32_16x16x32_bf16 v[54:57], v[142:145], v[166:169], v[54:57]
	v_mfma_f32_16x16x32_bf16 v[42:45], v[134:137], v[174:177], v[42:45]
	v_mfma_f32_16x16x32_bf16 v[38:41], v[142:145], v[174:177], v[38:41]
	v_mfma_f32_16x16x32_bf16 v[26:29], v[134:137], v[208:211], v[26:29]
	v_mfma_f32_16x16x32_bf16 v[22:25], v[142:145], v[208:211], v[22:25]
	v_mfma_f32_16x16x32_bf16 v[10:13], v[134:137], v[216:219], v[10:13]
	v_mfma_f32_16x16x32_bf16 v[6:9], v[142:145], v[216:219], v[6:9]
	s_setprio 0
	s_setprio 1
	v_mfma_f32_16x16x32_bf16 v[62:65], v[146:149], v[162:165], v[62:65]
	v_mfma_f32_16x16x32_bf16 v[50:53], v[154:157], v[162:165], v[50:53]
	v_mfma_f32_16x16x32_bf16 v[46:49], v[146:149], v[170:173], v[46:49]
	v_mfma_f32_16x16x32_bf16 v[34:37], v[154:157], v[170:173], v[34:37]
	v_mfma_f32_16x16x32_bf16 v[30:33], v[146:149], v[196:199], v[30:33]
	v_mfma_f32_16x16x32_bf16 v[18:21], v[154:157], v[196:199], v[18:21]
	v_mfma_f32_16x16x32_bf16 v[14:17], v[146:149], v[212:215], v[14:17]
	v_mfma_f32_16x16x32_bf16 v[2:5], v[154:157], v[212:215], v[2:5]
	v_mfma_f32_16x16x32_bf16 v[62:65], v[150:153], v[166:169], v[62:65]
	v_mfma_f32_16x16x32_bf16 v[50:53], v[158:161], v[166:169], v[50:53]
	v_mfma_f32_16x16x32_bf16 v[46:49], v[150:153], v[174:177], v[46:49]
	v_mfma_f32_16x16x32_bf16 v[34:37], v[158:161], v[174:177], v[34:37]
	v_mfma_f32_16x16x32_bf16 v[30:33], v[150:153], v[208:211], v[30:33]
	v_mfma_f32_16x16x32_bf16 v[18:21], v[158:161], v[208:211], v[18:21]
	v_mfma_f32_16x16x32_bf16 v[14:17], v[150:153], v[216:219], v[14:17]
	v_mfma_f32_16x16x32_bf16 v[2:5], v[158:161], v[216:219], v[2:5]
	s_setprio 0
	s_barrier
	s_add_i32 s53, s53, 2
	s_add_u32 s40, s40, 0x100
	s_addc_u32 s41, s41, 0
	s_add_u32 s45, s45, 0x100
	s_addc_u32 s52, s52, 0
	s_cmp_gt_u32 s53, 61
	s_cbranch_scc0 .LBB0_1127
	s_and_b64 vcc, exec, s[14:15]
	s_cbranch_vccz .LBB0_1130
	s_barrier
; #define GAS __attribute__((address_space(1)))
; __device__ __forceinline__ void unpack8(const v4u w, float (&f)[8]) { f[0] = bflo(w.x); f[1] = bfhi(w.x); f[2] = bflo(w.y); f[3] = bfhi(w.y); f[4] = bflo(w.z); f[5] = bfhi(w.z); f[6] = bflo(w.w); f[7] = bfhi(w.w); }
; __device__ __forceinline__ v4u pack8(const float (&f)[8]) { v4u w; w.x = pk2(f[0], f[1]); w.y = pk2(f[2], f[3]); w.z = pk2(f[4], f[5]); w.w = pk2(f[6], f[7]); return w; }
;     __device__ __forceinline__ void operator()(const af4 (&acc)[2][2][4][2], const pg8::Unit& u, int wr_, int wc_, int fr_, int fq_) const {
;         const int tid = my_tid(), lane = tid & 63, wid = __builtin_amdgcn_readfirstlane(tid >> 6), wr = wid >> 2, wc = wid & 3, fr = lane & 15, fq = lane >> 4;
;         (void)wr_; (void)wc_; (void)fr_; (void)fq_;
;         const int chbase = u.pn * 128, grp = u.pn / 6;
;         const bf16* wsg = wsb + (size_t)grp * 128 * 128;
;         const int chl = chbase + 32 * wc + 8 * (fr >> 2) + (fr & 3);
;         float lg[2], lb[2];
; #pragma unroll
;         for (int n = 0; n < 2; ++n) { lg[n] = lng[chl + 4 * n]; lb[n] = lnb[chl + 4 * n]; }
;         v4u raw[2][4];
;         auto load_raw = [&](int ai) {
; #pragma unroll
;             for (int ks = 0; ks < 4; ++ks)
; #pragma unroll
;                 for (int n = 0; n < 2; ++n) raw[n][ks] = *(const GAS v4u*)(VT + (size_t)(chl + 4 * n) * MLAT + u.pm * 256 + ai * 128 + 32 * ks + 8 * fq);
;         };
;         load_raw(0);
; #pragma unroll
;         for (int ai = 0; ai < 2; ++ai) {
;             const int tok0 = u.pm * 256 + ai * 128;
;             bf16x8 av[2][4];
; #pragma unroll
;             for (int ks = 0; ks < 4; ++ks) {
;                 const int j0 = tok0 + 32 * ks + 8 * fq;
;                 f32x4 st[4];
; #pragma unroll
;                 for (int q = 0; q < 4; ++q) st[q] = *(const GAS f32x4*)(stats + (size_t)(j0 + 2 * q) * 2);
; #pragma unroll
;                 for (int n = 0; n < 2; ++n) {
;                     float vf[8];
;                     unpack8(raw[n][ks], vf);
; #pragma unroll
;                     for (int q = 0; q < 4; ++q) { f32x2 t = {vf[2 * q], vf[2 * q + 1]}; t = t * (f32x2){st[q].z, st[q].w} + (f32x2){st[q].x, st[q].y}; t = t * lg[n] + lb[n]; vf[2 * q] = t.x; vf[2 * q + 1] = t.y; }
;                     av[n][ks] = __builtin_bit_cast(bf16x8, pack8(vf));
;                 }
.LBB0_1130:
	s_lshl_b32 s98, s6, 11
	s_sub_i32 s98, 0x20000, s98
	v_readfirstlane_b32 s99, v0
	s_nop 1
	s_cmpk_gt_u32 s99, 0x7f
	s_cbranch_scc1 .Lp11_st_nowr
	v_add_u32_e32 v233, 0x20000, v232
	s_nop 0
	ds_write_b128 v233, v[228:231]
.Lp11_st_nowr:
	s_waitcnt lgkmcnt(0)
	s_barrier
	v_mov_b32_e32 v164, v0
	s_mul_hi_i32 s23, s44, 0x2aaaaaab
	s_lshr_b32 s26, s23, 31
	v_readfirstlane_b32 s25, v164
	v_lshlrev_b32_e32 v130, 1, v164
	s_lshl_b32 s40, s44, 7
	s_add_i32 s44, s23, s26
	s_lshr_b32 s23, s25, 1
	v_and_b32_e32 v130, 24, v130
	v_and_b32_e32 v131, 3, v164
	s_ashr_i32 s45, s44, 31
	s_and_b32 s23, s23, 0x60
	v_or3_b32 v130, v131, v130, s40
	s_lshl_b64 s[26:27], s[44:45], 15
	v_or_b32_e32 v146, s23, v130
	v_or_b32_e32 v134, 4, v146
	s_add_u32 s52, s62, s26
	v_ashrrev_i32_e32 v147, 31, v146
	v_ashrrev_i32_e32 v135, 31, v134
	s_addc_u32 s53, s63, s27
	s_lshl_b32 s42, s6, 8
	v_lshrrev_b32_e32 v132, 1, v164
	v_lshlrev_b64 v[130:131], 15, v[146:147]
	s_ashr_i32 s43, s42, 31
	v_and_b32_e32 v209, 24, v132
	v_lshlrev_b64 v[134:135], 15, v[134:135]
	v_lshl_add_u64 v[130:131], s[50:51], 0, v[130:131]
	s_lshl_b64 s[26:27], s[42:43], 1
	v_lshl_add_u64 v[134:135], s[50:51], 0, v[134:135]
	v_or_b32_e32 v162, s42, v209
	v_lshl_add_u64 v[130:131], v[130:131], 0, s[26:27]
	v_lshlrev_b32_e32 v186, 1, v209
	v_lshl_add_u64 v[148:149], v[134:135], 0, s[26:27]
	v_ashrrev_i32_e32 v163, 31, v162
	v_lshl_add_u64 v[216:217], v[130:131], 0, v[186:187]
	v_lshl_add_u32 v150, v162, 3, s98
	v_lshl_add_u64 v[220:221], v[148:149], 0, v[186:187]
	global_load_dwordx4 v[130:133], v[216:217], off
	ds_read_b128 v[134:137], v150 offset:16
	ds_read_b128 v[138:141], v150
	ds_read_b128 v[142:145], v150 offset:48
	ds_read_b128 v[166:169], v150 offset:32
	global_load_dwordx4 v[170:173], v[220:221], off
	v_readlane_b32 s80, v254, 2
	v_readlane_b32 s81, v254, 3
	v_readlane_b32 s90, v254, 12
	v_readlane_b32 s91, v254, 13
	v_readlane_b32 s92, v254, 14
	v_readlane_b32 s93, v254, 15
	v_lshlrev_b64 v[146:147], 2, v[146:147]
	s_mov_b64 s[78:79], s[90:91]
	s_mov_b64 s[80:81], s[92:93]
	v_lshl_add_u64 v[148:149], s[78:79], 0, v[146:147]
	v_lshl_add_u64 v[146:147], s[80:81], 0, v[146:147]
	global_load_dword v206, v[146:147], off
	global_load_dword v208, v[148:149], off
	global_load_dword v202, v[148:149], off offset:16
	global_load_dword v204, v[146:147], off offset:16
	global_load_dwordx4 v[174:177], v[216:217], off offset:64
	global_load_dwordx4 v[150:153], v[216:217], off offset:128
	global_load_dwordx4 v[158:161], v[216:217], off offset:192
	global_load_dwordx4 v[196:199], v[220:221], off offset:64
	s_nop 0
	global_load_dwordx4 v[146:149], v[220:221], off offset:128
	global_load_dwordx4 v[154:157], v[220:221], off offset:192
	s_ashr_i32 s6, s25, 2
	s_andn2_b32 s6, s6, 63
	v_pk_mul_f32 v[226:227], v[126:127], s[20:21] op_sel_hi:[1,0]
	v_pk_mul_f32 v[234:235], v[122:123], v[126:127]
	v_pk_mul_f32 v[126:127], v[128:129], s[20:21] op_sel_hi:[1,0]
	v_pk_mul_f32 v[236:237], v[124:125], v[128:129]
	v_pk_mul_f32 v[128:129], v[120:121], v[120:121]
	v_pk_mul_f32 v[228:229], v[118:119], v[118:119]
	v_pk_mul_f32 v[230:231], v[114:115], s[20:21] op_sel_hi:[1,0]
	v_pk_mul_f32 v[238:239], v[118:119], v[114:115]
	v_pk_mul_f32 v[114:115], v[116:117], s[20:21] op_sel_hi:[1,0]
	v_pk_mul_f32 v[240:241], v[120:121], v[116:117]
	v_exp_f32_e32 v126, v126
	v_exp_f32_e32 v127, v127
	v_exp_f32_e32 v114, v114
	v_exp_f32_e32 v115, v115
	s_ashr_i32 s41, s40, 31
	v_pk_add_f32 v[126:127], v[126:127], 1.0 op_sel_hi:[1,0]
	s_lshl_b64 s[40:41], s[40:41], 1
	v_pk_add_f32 v[114:115], v[114:115], 1.0 op_sel_hi:[1,0]
	v_pk_mul_f32 v[252:253], v[102:103], v[98:99]
	v_pk_mul_f32 v[192:193], v[104:105], v[100:101]
	s_andn2_b64 vcc, exec, s[4:5]
	v_readlane_b32 s82, v254, 4
	v_readlane_b32 s83, v254, 5
	v_readlane_b32 s84, v254, 6
	v_readlane_b32 s85, v254, 7
	v_readlane_b32 s86, v254, 8
	v_readlane_b32 s87, v254, 9
	v_readlane_b32 s88, v254, 10
	v_readlane_b32 s89, v254, 11
	v_readlane_b32 s94, v254, 16
	v_readlane_b32 s95, v254, 17
	s_waitcnt vmcnt(0)
	s_waitcnt lgkmcnt(0)
	v_lshlrev_b32_e32 v200, 16, v130
	v_and_b32_e32 v201, 0xffff0000, v130
	v_lshlrev_b32_e32 v212, 16, v170
	v_and_b32_e32 v213, 0xffff0000, v170
	v_lshlrev_b32_e32 v130, 16, v131
	v_and_b32_e32 v131, 0xffff0000, v131
	v_lshlrev_b32_e32 v210, 16, v132
	v_and_b32_e32 v211, 0xffff0000, v132
	v_lshlrev_b32_e32 v132, 16, v133
	v_and_b32_e32 v133, 0xffff0000, v133
	v_pk_fma_f32 v[200:201], v[140:141], v[200:201], v[138:139]
	v_lshlrev_b32_e32 v170, 16, v171
	v_and_b32_e32 v171, 0xffff0000, v171
	v_pk_fma_f32 v[138:139], v[140:141], v[212:213], v[138:139]
	v_pk_fma_f32 v[130:131], v[136:137], v[130:131], v[134:135]
	v_pk_fma_f32 v[210:211], v[168:169], v[210:211], v[166:167]
	v_pk_fma_f32 v[132:133], v[144:145], v[132:133], v[142:143]
	v_lshlrev_b32_e32 v214, 16, v172
	v_and_b32_e32 v215, 0xffff0000, v172
	v_lshlrev_b32_e32 v172, 16, v173
	v_and_b32_e32 v173, 0xffff0000, v173
	v_pk_fma_f32 v[134:135], v[136:137], v[170:171], v[134:135]
	v_pk_fma_f32 v[138:139], v[202:203], v[138:139], v[204:205] op_sel_hi:[0,1,0]
	v_pk_fma_f32 v[200:201], v[208:209], v[200:201], v[206:207] op_sel_hi:[0,1,0]
	v_pk_fma_f32 v[218:219], v[208:209], v[130:131], v[206:207] op_sel_hi:[0,1,0]
	v_pk_fma_f32 v[210:211], v[208:209], v[210:211], v[206:207] op_sel_hi:[0,1,0]
	v_pk_fma_f32 v[222:223], v[208:209], v[132:133], v[206:207] op_sel_hi:[0,1,0]
	v_pk_fma_f32 v[140:141], v[144:145], v[172:173], v[142:143]
	v_cvt_pk_bf16_f32 v130, v200, v201
	v_cvt_pk_bf16_f32 v131, v218, v219
	v_cvt_pk_bf16_f32 v132, v210, v211
	v_cvt_pk_bf16_f32 v133, v222, v223
	v_pk_fma_f32 v[142:143], v[202:203], v[134:135], v[204:205] op_sel_hi:[0,1,0]
; #define GAS __attribute__((address_space(1)))
; __device__ __forceinline__ void unpack8(const v4u w, float (&f)[8]) { f[0] = bflo(w.x); f[1] = bfhi(w.x); f[2] = bflo(w.y); f[3] = bfhi(w.y); f[4] = bflo(w.z); f[5] = bfhi(w.z); f[6] = bflo(w.w); f[7] = bfhi(w.w); }
; __device__ __forceinline__ v4u pack8(const float (&f)[8]) { v4u w; w.x = pk2(f[0], f[1]); w.y = pk2(f[2], f[3]); w.z = pk2(f[4], f[5]); w.w = pk2(f[6], f[7]); return w; }
;     __device__ __forceinline__ void operator()(const af4 (&acc)[2][2][4][2], const pg8::Unit& u, int wr_, int wc_, int fr_, int fq_) const {
;     ...
;             for (int ks = 0; ks < 4; ++ks) {
;                 const int j0 = tok0 + 32 * ks + 8 * fq;
;                 f32x4 st[4];
; #pragma unroll
;                 for (int q = 0; q < 4; ++q) st[q] = *(const GAS f32x4*)(stats + (size_t)(j0 + 2 * q) * 2);
; #pragma unroll
;                 for (int n = 0; n < 2; ++n) {
;                     float vf[8];
;                     unpack8(raw[n][ks], vf);
; #pragma unroll
;                     for (int q = 0; q < 4; ++q) { f32x2 t = {vf[2 * q], vf[2 * q + 1]}; t = t * (f32x2){st[q].z, st[q].w} + (f32x2){st[q].x, st[q].y}; t = t * lg[n] + lb[n]; vf[2 * q] = t.x; vf[2 * q + 1] = t.y; }
;                     av[n][ks] = __builtin_bit_cast(bf16x8, pack8(vf));
;                 }
	v_cvt_pk_bf16_f32 v134, v138, v139
	v_or_b32_e32 v138, 32, v162
	v_pk_fma_f32 v[136:137], v[168:169], v[214:215], v[166:167]
	v_ashrrev_i32_e32 v139, 31, v138
	v_pk_fma_f32 v[136:137], v[202:203], v[136:137], v[204:205] op_sel_hi:[0,1,0]
	v_pk_fma_f32 v[140:141], v[202:203], v[140:141], v[204:205] op_sel_hi:[0,1,0]
	v_lshl_add_u32 v170, v138, 3, s98
	v_cvt_pk_bf16_f32 v135, v142, v143
	v_cvt_pk_bf16_f32 v136, v136, v137
	v_cvt_pk_bf16_f32 v137, v140, v141
	ds_read_b128 v[138:141], v170
	ds_read_b128 v[142:145], v170 offset:16
	ds_read_b128 v[166:169], v170 offset:32
	s_nop 0
	ds_read_b128 v[170:173], v170 offset:48
	v_or_b32_e32 v200, 64, v162
	v_lshlrev_b32_e32 v210, 16, v174
	v_and_b32_e32 v211, 0xffff0000, v174
	v_lshlrev_b32_e32 v174, 16, v175
	v_and_b32_e32 v175, 0xffff0000, v175
	v_lshlrev_b32_e32 v212, 16, v176
	v_and_b32_e32 v213, 0xffff0000, v176
	v_lshlrev_b32_e32 v176, 16, v177
	v_and_b32_e32 v177, 0xffff0000, v177
	v_lshlrev_b32_e32 v214, 16, v196
	v_and_b32_e32 v215, 0xffff0000, v196
	v_lshlrev_b32_e32 v196, 16, v197
	v_and_b32_e32 v197, 0xffff0000, v197
	v_lshlrev_b32_e32 v218, 16, v198
	v_and_b32_e32 v219, 0xffff0000, v198
	v_lshlrev_b32_e32 v198, 16, v199
	v_and_b32_e32 v199, 0xffff0000, v199
	v_ashrrev_i32_e32 v201, 31, v200
	v_lshl_add_u32 v200, v200, 3, s98
	v_or_b32_e32 v162, 0x60, v162
	v_ashrrev_i32_e32 v163, 31, v162
	v_lshl_add_u32 v162, v162, 3, s98
	v_and_b32_e32 v165, 0xffff0000, v160
	s_waitcnt lgkmcnt(3)
	v_pk_fma_f32 v[210:211], v[140:141], v[210:211], v[138:139]
	s_waitcnt lgkmcnt(2)
	v_pk_fma_f32 v[174:175], v[144:145], v[174:175], v[142:143]
	s_waitcnt lgkmcnt(1)
	v_pk_fma_f32 v[212:213], v[168:169], v[212:213], v[166:167]
	s_waitcnt lgkmcnt(0)
	v_pk_fma_f32 v[176:177], v[172:173], v[176:177], v[170:171]
	v_pk_fma_f32 v[138:139], v[140:141], v[214:215], v[138:139]
	v_pk_fma_f32 v[140:141], v[144:145], v[196:197], v[142:143]
	v_pk_fma_f32 v[142:143], v[168:169], v[218:219], v[166:167]
	v_pk_fma_f32 v[144:145], v[172:173], v[198:199], v[170:171]
	v_pk_fma_f32 v[166:167], v[208:209], v[210:211], v[206:207] op_sel_hi:[0,1,0]
	v_pk_fma_f32 v[168:169], v[208:209], v[174:175], v[206:207] op_sel_hi:[0,1,0]
	v_pk_fma_f32 v[170:171], v[208:209], v[212:213], v[206:207] op_sel_hi:[0,1,0]
	v_pk_fma_f32 v[172:173], v[208:209], v[176:177], v[206:207] op_sel_hi:[0,1,0]
	v_pk_fma_f32 v[138:139], v[202:203], v[138:139], v[204:205] op_sel_hi:[0,1,0]
	v_pk_fma_f32 v[140:141], v[202:203], v[140:141], v[204:205] op_sel_hi:[0,1,0]
	v_pk_fma_f32 v[174:175], v[202:203], v[142:143], v[204:205] op_sel_hi:[0,1,0]
	v_pk_fma_f32 v[176:177], v[202:203], v[144:145], v[204:205] op_sel_hi:[0,1,0]
	v_cvt_pk_bf16_f32 v142, v166, v167
	v_cvt_pk_bf16_f32 v143, v168, v169
	v_cvt_pk_bf16_f32 v144, v170, v171
	v_cvt_pk_bf16_f32 v145, v172, v173
	v_cvt_pk_bf16_f32 v138, v138, v139
	v_cvt_pk_bf16_f32 v139, v140, v141
	v_cvt_pk_bf16_f32 v140, v174, v175
	v_cvt_pk_bf16_f32 v141, v176, v177
	ds_read_b128 v[166:169], v200
	ds_read_b128 v[170:173], v200 offset:16
	ds_read_b128 v[174:177], v200 offset:32
	ds_read_b128 v[196:199], v200 offset:48
	v_lshlrev_b32_e32 v200, 16, v150
	v_and_b32_e32 v201, 0xffff0000, v150
	v_lshlrev_b32_e32 v150, 16, v151
	v_and_b32_e32 v151, 0xffff0000, v151
	v_lshlrev_b32_e32 v210, 16, v152
	v_and_b32_e32 v211, 0xffff0000, v152
	v_lshlrev_b32_e32 v152, 16, v153
	v_and_b32_e32 v153, 0xffff0000, v153
	v_lshlrev_b32_e32 v212, 16, v146
	v_and_b32_e32 v213, 0xffff0000, v146
	v_lshlrev_b32_e32 v146, 16, v147
	v_and_b32_e32 v147, 0xffff0000, v147
	v_lshlrev_b32_e32 v214, 16, v148
	v_and_b32_e32 v215, 0xffff0000, v148
	v_lshlrev_b32_e32 v148, 16, v149
	v_and_b32_e32 v149, 0xffff0000, v149
	v_lshl_add_u64 v[218:219], s[52:53], 0, v[186:187]
	s_waitcnt lgkmcnt(3)
	v_pk_fma_f32 v[200:201], v[168:169], v[200:201], v[166:167]
	s_waitcnt lgkmcnt(2)
	v_pk_fma_f32 v[150:151], v[172:173], v[150:151], v[170:171]
	s_waitcnt lgkmcnt(1)
	v_pk_fma_f32 v[210:211], v[176:177], v[210:211], v[174:175]
	s_waitcnt lgkmcnt(0)
	v_pk_fma_f32 v[152:153], v[198:199], v[152:153], v[196:197]
	v_pk_fma_f32 v[166:167], v[168:169], v[212:213], v[166:167]
	v_pk_fma_f32 v[146:147], v[172:173], v[146:147], v[170:171]
	v_pk_fma_f32 v[168:169], v[176:177], v[214:215], v[174:175]
	v_pk_fma_f32 v[148:149], v[198:199], v[148:149], v[196:197]
	v_pk_fma_f32 v[170:171], v[208:209], v[200:201], v[206:207] op_sel_hi:[0,1,0]
	v_pk_fma_f32 v[172:173], v[208:209], v[150:151], v[206:207] op_sel_hi:[0,1,0]
	v_pk_fma_f32 v[174:175], v[208:209], v[210:211], v[206:207] op_sel_hi:[0,1,0]
	v_pk_fma_f32 v[176:177], v[208:209], v[152:153], v[206:207] op_sel_hi:[0,1,0]
	v_pk_fma_f32 v[166:167], v[202:203], v[166:167], v[204:205] op_sel_hi:[0,1,0]
	v_pk_fma_f32 v[196:197], v[202:203], v[146:147], v[204:205] op_sel_hi:[0,1,0]
	v_pk_fma_f32 v[168:169], v[202:203], v[168:169], v[204:205] op_sel_hi:[0,1,0]
	v_pk_fma_f32 v[198:199], v[202:203], v[148:149], v[204:205] op_sel_hi:[0,1,0]
	v_cvt_pk_bf16_f32 v150, v170, v171
	v_cvt_pk_bf16_f32 v151, v172, v173
	v_cvt_pk_bf16_f32 v152, v174, v175
	v_cvt_pk_bf16_f32 v153, v176, v177
	v_cvt_pk_bf16_f32 v146, v166, v167
	v_cvt_pk_bf16_f32 v147, v196, v197
	v_cvt_pk_bf16_f32 v148, v168, v169
	v_cvt_pk_bf16_f32 v149, v198, v199
	ds_read_b128 v[166:169], v162
	ds_read_b128 v[170:173], v162 offset:16
	ds_read_b128 v[174:177], v162 offset:32
	ds_read_b128 v[196:199], v162 offset:48
	v_and_or_b32 v210, v164, 15, s6
	v_lshl_add_u32 v162, s44, 7, v210
	v_ashrrev_i32_e32 v163, 31, v162
	v_lshl_add_u64 v[200:201], v[162:163], 2, s[76:77]
	v_lshlrev_b32_e32 v162, 16, v158
	v_and_b32_e32 v163, 0xffff0000, v158
	v_lshlrev_b32_e32 v164, 16, v160
	v_lshlrev_b32_e32 v212, 16, v154
	v_and_b32_e32 v213, 0xffff0000, v154
	v_lshlrev_b32_e32 v154, 16, v155
	v_and_b32_e32 v155, 0xffff0000, v155
	v_lshlrev_b32_e32 v158, 16, v159
	v_and_b32_e32 v159, 0xffff0000, v159
	v_lshlrev_b32_e32 v160, 16, v161
	v_and_b32_e32 v161, 0xffff0000, v161
	v_lshlrev_b32_e32 v214, 16, v156
	v_and_b32_e32 v215, 0xffff0000, v156
	v_lshlrev_b32_e32 v156, 16, v157
	v_and_b32_e32 v157, 0xffff0000, v157
	v_ashrrev_i32_e32 v211, 31, v210
	s_lshl_b32 s6, s23, 1
	s_or_b32 s23, s42, 0x80
	s_waitcnt lgkmcnt(3)
; #define GAS __attribute__((address_space(1)))
; __device__ __forceinline__ float fexp2(float x) { return __builtin_amdgcn_exp2f(x); }
;     __device__ __forceinline__ void operator()(const af4 (&acc)[2][2][4][2], const pg8::Unit& u, int wr_, int wc_, int fr_, int fq_) const {
;     ...
;                 for (int n = 0; n < 2; ++n) {
;                     float vf[8];
;                     unpack8(raw[n][ks], vf);
; #pragma unroll
;                     for (int q = 0; q < 4; ++q) { f32x2 t = {vf[2 * q], vf[2 * q + 1]}; t = t * (f32x2){st[q].z, st[q].w} + (f32x2){st[q].x, st[q].y}; t = t * lg[n] + lb[n]; vf[2 * q] = t.x; vf[2 * q + 1] = t.y; }
;                     av[n][ks] = __builtin_bit_cast(bf16x8, pack8(vf));
;                 }
;             }
; #pragma unroll
;             for (int m = 0; m < 4; ++m) {
;                 if (ai == 0 && m == 0) load_raw(1);
;                 const int it = wr * 64 + m * 16 + fr;
;                 bf16x8 wf[4];
; #pragma unroll
;                 for (int ks = 0; ks < 4; ++ks) wf[ks] = *(const GAS bf16x8*)(wsg + (size_t)it * 128 + 32 * ks + 8 * fq);
;                 const float bsi = bs[grp * 128 + it];
;                 af4 vm[2] = {(af4){bsi, bsi, bsi, bsi}, (af4){bsi, bsi, bsi, bsi}};
; #pragma unroll
;                 for (int ks = 0; ks < 4; ++ks) {
; #pragma unroll
;                     for (int n = 0; n < 2; ++n) vm[n] = __builtin_amdgcn_mfma_f32_16x16x32_bf16(av[n][ks], wf[ks], vm[n], 0, 0, 0);
;                 }
;                 float o[8];
; #pragma unroll
;                 for (int n = 0; n < 2; ++n)
; #pragma unroll
;                     for (int e = 0; e < 4; e += 2) {
;                         const f32x2 uu = {acc[ai][0][m][n][e], acc[ai][0][m][n][e + 1]}, gg = {acc[ai][1][m][n][e], acc[ai][1][m][n][e + 1]}, vv = {vm[n][e], vm[n][e + 1]};
;                         const f32x2 ar = uu * (uu * uu * (-2.302208198f * 0.044715f) + (-2.302208198f));
;                         const f32x2 gs = gg * (-1.4426950408889634f);
;                         const f32x2 ea = {fexp2(ar.x), fexp2(ar.y)}, eb = {fexp2(gs.x), fexp2(gs.y)};
;                         const f32x2 q = eb + 1.0f, den = ea * q + q;
;                         const f32x2 r = {frcp(den.x), frcp(den.y)};
;                         const f32x2 w = (uu * gg) * vv * r;
;                         o[4 * n + e] = w.x; o[4 * n + e + 1] = w.y; }
	v_pk_fma_f32 v[162:163], v[168:169], v[162:163], v[166:167]
	s_waitcnt lgkmcnt(2)
	v_pk_fma_f32 v[154:155], v[172:173], v[154:155], v[170:171]
	s_waitcnt lgkmcnt(1)
	v_pk_fma_f32 v[164:165], v[176:177], v[164:165], v[174:175]
	v_pk_fma_f32 v[158:159], v[172:173], v[158:159], v[170:171]
	s_waitcnt lgkmcnt(0)
	v_pk_fma_f32 v[160:161], v[198:199], v[160:161], v[196:197]
	v_pk_fma_f32 v[166:167], v[168:169], v[212:213], v[166:167]
	v_pk_fma_f32 v[168:169], v[176:177], v[214:215], v[174:175]
	v_pk_fma_f32 v[156:157], v[198:199], v[156:157], v[196:197]
	v_pk_fma_f32 v[162:163], v[208:209], v[162:163], v[206:207] op_sel_hi:[0,1,0]
	v_pk_fma_f32 v[164:165], v[208:209], v[164:165], v[206:207] op_sel_hi:[0,1,0]
	v_pk_fma_f32 v[154:155], v[202:203], v[154:155], v[204:205] op_sel_hi:[0,1,0]
	v_pk_fma_f32 v[158:159], v[208:209], v[158:159], v[206:207] op_sel_hi:[0,1,0]
	v_pk_fma_f32 v[160:161], v[208:209], v[160:161], v[206:207] op_sel_hi:[0,1,0]
	v_pk_fma_f32 v[170:171], v[202:203], v[166:167], v[204:205] op_sel_hi:[0,1,0]
	v_pk_fma_f32 v[172:173], v[202:203], v[168:169], v[204:205] op_sel_hi:[0,1,0]
	v_pk_fma_f32 v[156:157], v[202:203], v[156:157], v[204:205] op_sel_hi:[0,1,0]
	v_cvt_pk_bf16_f32 v166, v162, v163
	v_cvt_pk_bf16_f32 v167, v158, v159
	v_cvt_pk_bf16_f32 v168, v164, v165
	v_cvt_pk_bf16_f32 v169, v160, v161
	v_cvt_pk_bf16_f32 v162, v170, v171
	v_cvt_pk_bf16_f32 v163, v154, v155
	v_cvt_pk_bf16_f32 v164, v172, v173
	v_cvt_pk_bf16_f32 v165, v156, v157
	global_load_dword v154, v[200:201], off
	v_lshlrev_b64 v[156:157], 8, v[210:211]
	v_lshl_add_u64 v[214:215], v[218:219], 0, v[156:157]
	global_load_dwordx4 v[158:161], v[214:215], off
	global_load_dwordx4 v[170:173], v[214:215], off offset:64
	global_load_dwordx4 v[174:177], v[214:215], off offset:128
	global_load_dwordx4 v[222:225], v[214:215], off offset:192
	v_pk_mul_f32 v[156:157], v[124:125], v[124:125]
	v_pk_mul_f32 v[212:213], v[122:123], v[122:123]
	v_mov_b64_e32 v[196:197], s[18:19]
	v_pk_fma_f32 v[116:117], v[212:213], s[16:17], v[196:197] op_sel_hi:[1,0,0] neg_lo:[1,0,0] neg_hi:[1,0,0]
	v_exp_f32_e32 v212, v226
	v_exp_f32_e32 v213, v227
	v_pk_fma_f32 v[156:157], v[156:157], s[16:17], v[196:197] op_sel_hi:[1,0,0] neg_lo:[1,0,0] neg_hi:[1,0,0]
	v_pk_fma_f32 v[226:227], v[228:229], s[16:17], v[196:197] op_sel_hi:[1,0,0] neg_lo:[1,0,0] neg_hi:[1,0,0]
	v_pk_fma_f32 v[128:129], v[128:129], s[16:17], v[196:197] op_sel_hi:[1,0,0] neg_lo:[1,0,0] neg_hi:[1,0,0]
	v_exp_f32_e32 v228, v230
	v_exp_f32_e32 v229, v231
	v_pk_mul_f32 v[116:117], v[122:123], v[116:117]
	v_pk_mul_f32 v[122:123], v[124:125], v[156:157]
	v_pk_mul_f32 v[118:119], v[118:119], v[226:227]
	v_pk_mul_f32 v[120:121], v[120:121], v[128:129]
	v_exp_f32_e32 v116, v116
	v_exp_f32_e32 v117, v117
	v_exp_f32_e32 v122, v122
	v_exp_f32_e32 v123, v123
	v_exp_f32_e32 v118, v118
	v_exp_f32_e32 v119, v119
	v_exp_f32_e32 v120, v120
	v_exp_f32_e32 v121, v121
	v_pk_add_f32 v[124:125], v[212:213], 1.0 op_sel_hi:[1,0]
	v_pk_add_f32 v[128:129], v[228:229], 1.0 op_sel_hi:[1,0]
	v_pk_fma_f32 v[124:125], v[116:117], v[124:125], v[124:125]
	v_pk_fma_f32 v[122:123], v[122:123], v[126:127], v[126:127]
	v_pk_fma_f32 v[126:127], v[118:119], v[128:129], v[128:129]
	v_pk_fma_f32 v[128:129], v[120:121], v[114:115], v[114:115]
	v_mov_b64_e32 v[198:199], s[56:57]
	v_rcp_f32_e32 v244, v122
	v_add_u32_e32 v122, s42, v210
	v_rcp_f32_e32 v245, v123
	v_mad_i64_i32 v[122:123], s[26:27], v122, s61, v[198:199]
	v_lshl_add_u64 v[122:123], v[122:123], 0, s[40:41]
	v_lshl_add_u64 v[122:123], v[122:123], 0, s[6:7]
	v_rcp_f32_e32 v242, v124
	v_rcp_f32_e32 v243, v125
	v_rcp_f32_e32 v246, v126
	v_rcp_f32_e32 v247, v127
	v_rcp_f32_e32 v248, v128
	v_rcp_f32_e32 v249, v129
	v_lshl_add_u64 v[250:251], v[122:123], 0, v[186:187]
	v_or_b32_e32 v212, 16, v210
	v_ashrrev_i32_e32 v213, 31, v212
	v_add_u32_e32 v211, s42, v212
	s_waitcnt vmcnt(4)
	v_mov_b32_e32 v155, v154
	v_mov_b32_e32 v156, v154
	v_mov_b32_e32 v157, v154
	s_waitcnt vmcnt(3)
	s_nop 0
	v_mfma_f32_16x16x32_bf16 v[114:117], v[130:133], v[158:161], v[154:157]
	v_mfma_f32_16x16x32_bf16 v[118:121], v[134:137], v[158:161], v[154:157]
	s_waitcnt vmcnt(2)
	v_mfma_f32_16x16x32_bf16 v[114:117], v[142:145], v[170:173], v[114:117]
	v_mfma_f32_16x16x32_bf16 v[118:121], v[138:141], v[170:173], v[118:121]
	s_waitcnt vmcnt(1)
	v_mfma_f32_16x16x32_bf16 v[114:117], v[150:153], v[174:177], v[114:117]
	v_mfma_f32_16x16x32_bf16 v[226:229], v[146:149], v[174:177], v[118:121]
	global_load_dwordx4 v[174:177], v[216:217], off offset:256
	global_load_dwordx4 v[158:161], v[216:217], off offset:320
	global_load_dwordx4 v[170:173], v[220:221], off offset:256
	global_load_dwordx4 v[154:157], v[220:221], off offset:320
	s_waitcnt vmcnt(4)
; #define GAS __attribute__((address_space(1)))
; __device__ __forceinline__ v4u pack8(const float (&f)[8]) { v4u w; w.x = pk2(f[0], f[1]); w.y = pk2(f[2], f[3]); w.z = pk2(f[4], f[5]); w.w = pk2(f[6], f[7]); return w; }
; __device__ __forceinline__ float fexp2(float x) { return __builtin_amdgcn_exp2f(x); }
; __device__ __forceinline__ float frcp(float x) { return __builtin_amdgcn_rcpf(x); }
;     __device__ __forceinline__ void operator()(const af4 (&acc)[2][2][4][2], const pg8::Unit& u, int wr_, int wc_, int fr_, int fq_) const {
;     ...
;             for (int m = 0; m < 4; ++m) {
;                 if (ai == 0 && m == 0) load_raw(1);
;                 const int it = wr * 64 + m * 16 + fr;
;                 bf16x8 wf[4];
; #pragma unroll
;                 for (int ks = 0; ks < 4; ++ks) wf[ks] = *(const GAS bf16x8*)(wsg + (size_t)it * 128 + 32 * ks + 8 * fq);
;                 const float bsi = bs[grp * 128 + it];
;                 af4 vm[2] = {(af4){bsi, bsi, bsi, bsi}, (af4){bsi, bsi, bsi, bsi}};
; #pragma unroll
;                 for (int ks = 0; ks < 4; ++ks) {
; #pragma unroll
;                     for (int n = 0; n < 2; ++n) vm[n] = __builtin_amdgcn_mfma_f32_16x16x32_bf16(av[n][ks], wf[ks], vm[n], 0, 0, 0);
;                 }
;                 float o[8];
; #pragma unroll
;                 for (int n = 0; n < 2; ++n)
; #pragma unroll
;                     for (int e = 0; e < 4; e += 2) {
;                         const f32x2 uu = {acc[ai][0][m][n][e], acc[ai][0][m][n][e + 1]}, gg = {acc[ai][1][m][n][e], acc[ai][1][m][n][e + 1]}, vv = {vm[n][e], vm[n][e + 1]};
;                         const f32x2 ar = uu * (uu * uu * (-2.302208198f * 0.044715f) + (-2.302208198f));
;                         const f32x2 gs = gg * (-1.4426950408889634f);
;                         const f32x2 ea = {fexp2(ar.x), fexp2(ar.y)}, eb = {fexp2(gs.x), fexp2(gs.y)};
;                         const f32x2 q = eb + 1.0f, den = ea * q + q;
;                         const f32x2 r = {frcp(den.x), frcp(den.y)};
;                         const f32x2 w = (uu * gg) * vv * r;
;                         o[4 * n + e] = w.x; o[4 * n + e + 1] = w.y; }
;                 *(GAS v4u*)(Y + (size_t)(tok0 + it) * CW + chbase + 32 * wc + 8 * fq) = pack8(o);
	v_mfma_f32_16x16x32_bf16 v[230:233], v[166:169], v[222:225], v[114:117]
	global_load_dwordx4 v[126:129], v[216:217], off offset:384
	global_load_dwordx4 v[118:121], v[216:217], off offset:448
	global_load_dwordx4 v[122:125], v[220:221], off offset:384
	global_load_dwordx4 v[114:117], v[220:221], off offset:448
	v_mfma_f32_16x16x32_bf16 v[220:223], v[162:165], v[222:225], v[226:229]
	s_nop 2
	v_mul_f32_e64 v216, v234, v230
	v_mul_f32_e64 v217, v235, v231
	v_pk_mul_f32 v[224:225], v[236:237], v[232:233]
	v_pk_mul_f32 v[216:217], v[242:243], v[216:217]
	v_pk_mul_f32 v[224:225], v[244:245], v[224:225]
	v_pk_mul_f32 v[242:243], v[110:111], s[20:21] op_sel_hi:[1,0]
	v_pk_mul_f32 v[220:221], v[238:239], v[220:221]
	v_pk_mul_f32 v[222:223], v[240:241], v[222:223]
	v_pk_mul_f32 v[226:227], v[246:247], v[220:221]
	v_pk_mul_f32 v[228:229], v[248:249], v[222:223]
	v_cvt_pk_bf16_f32 v220, v216, v217
	v_cvt_pk_bf16_f32 v221, v224, v225
	v_cvt_pk_bf16_f32 v222, v226, v227
	v_lshlrev_b64 v[216:217], 8, v[212:213]
	v_cvt_pk_bf16_f32 v223, v228, v229
	global_store_dwordx4 v[250:251], v[220:223], off
	global_load_dword v220, v[200:201], off offset:64
	v_lshl_add_u64 v[216:217], v[218:219], 0, v[216:217]
	global_load_dwordx4 v[224:227], v[216:217], off
	global_load_dwordx4 v[228:231], v[216:217], off offset:64
	global_load_dwordx4 v[232:235], v[216:217], off offset:128
	global_load_dwordx4 v[236:239], v[216:217], off offset:192
	v_pk_mul_f32 v[222:223], v[108:109], v[108:109]
	v_pk_mul_f32 v[240:241], v[106:107], v[106:107]
	v_pk_mul_f32 v[244:245], v[112:113], s[20:21] op_sel_hi:[1,0]
	v_pk_mul_f32 v[248:249], v[102:103], v[102:103]
	v_pk_mul_f32 v[250:251], v[98:99], s[20:21] op_sel_hi:[1,0]
	v_pk_mul_f32 v[98:99], v[100:101], s[20:21] op_sel_hi:[1,0]
	v_pk_fma_f32 v[100:101], v[240:241], s[16:17], v[196:197] op_sel_hi:[1,0,0] neg_lo:[1,0,0] neg_hi:[1,0,0]
	v_pk_fma_f32 v[222:223], v[222:223], s[16:17], v[196:197] op_sel_hi:[1,0,0] neg_lo:[1,0,0] neg_hi:[1,0,0]
	v_exp_f32_e32 v240, v242
	v_exp_f32_e32 v241, v243
	v_exp_f32_e32 v242, v244
	v_exp_f32_e32 v243, v245
	v_pk_fma_f32 v[244:245], v[248:249], s[16:17], v[196:197] op_sel_hi:[1,0,0] neg_lo:[1,0,0] neg_hi:[1,0,0]
	v_exp_f32_e32 v248, v250
	v_exp_f32_e32 v249, v251
	v_exp_f32_e32 v250, v98
	v_exp_f32_e32 v251, v99
	v_pk_mul_f32 v[98:99], v[106:107], v[100:101]
	v_pk_mul_f32 v[100:101], v[108:109], v[222:223]
	v_pk_mul_f32 v[110:111], v[106:107], v[110:111]
	v_pk_mul_f32 v[112:113], v[108:109], v[112:113]
	v_pk_mul_f32 v[246:247], v[104:105], v[104:105]
	v_exp_f32_e32 v106, v98
	v_exp_f32_e32 v107, v99
	v_exp_f32_e32 v108, v100
	v_exp_f32_e32 v109, v101
	v_pk_fma_f32 v[246:247], v[246:247], s[16:17], v[196:197] op_sel_hi:[1,0,0] neg_lo:[1,0,0] neg_hi:[1,0,0]
	v_pk_mul_f32 v[102:103], v[102:103], v[244:245]
	v_pk_mul_f32 v[104:105], v[104:105], v[246:247]
	v_exp_f32_e32 v244, v102
	v_exp_f32_e32 v245, v103
	v_exp_f32_e32 v246, v104
	v_exp_f32_e32 v247, v105
	v_pk_add_f32 v[102:103], v[240:241], 1.0 op_sel_hi:[1,0]
	v_pk_add_f32 v[104:105], v[242:243], 1.0 op_sel_hi:[1,0]
	v_pk_fma_f32 v[106:107], v[106:107], v[102:103], v[102:103]
	v_pk_fma_f32 v[108:109], v[108:109], v[104:105], v[104:105]
	v_pk_add_f32 v[240:241], v[248:249], 1.0 op_sel_hi:[1,0]
	v_pk_add_f32 v[242:243], v[250:251], 1.0 op_sel_hi:[1,0]
	s_waitcnt vmcnt(4)
	v_mov_b32_e32 v221, v220
	v_mov_b32_e32 v222, v220
	v_mov_b32_e32 v223, v220
	s_waitcnt vmcnt(3)
	s_nop 0
	v_mfma_f32_16x16x32_bf16 v[98:101], v[130:133], v[224:227], v[220:223]
	v_mfma_f32_16x16x32_bf16 v[102:105], v[134:137], v[224:227], v[220:223]
	v_rcp_f32_e32 v224, v106
	v_rcp_f32_e32 v225, v107
	v_rcp_f32_e32 v226, v108
	s_waitcnt vmcnt(2)
	v_mfma_f32_16x16x32_bf16 v[98:101], v[142:145], v[228:231], v[98:101]
	v_rcp_f32_e32 v227, v109
	v_pk_fma_f32 v[220:221], v[244:245], v[240:241], v[240:241]
	v_pk_fma_f32 v[222:223], v[246:247], v[242:243], v[242:243]
	v_mfma_f32_16x16x32_bf16 v[102:105], v[138:141], v[228:231], v[102:105]
	v_rcp_f32_e32 v220, v220
	v_rcp_f32_e32 v221, v221
	v_rcp_f32_e32 v222, v222
	s_waitcnt vmcnt(1)
	v_mfma_f32_16x16x32_bf16 v[106:109], v[150:153], v[232:235], v[98:101]
	v_rcp_f32_e32 v223, v223
	v_mad_i64_i32 v[228:229], s[26:27], v211, s61, v[198:199]
	v_mfma_f32_16x16x32_bf16 v[100:103], v[146:149], v[232:235], v[102:105]
	v_or_b32_e32 v98, 32, v210
	v_ashrrev_i32_e32 v99, 31, v98
	v_pk_mul_f32 v[234:235], v[86:87], v[86:87]
	s_waitcnt vmcnt(0)
; #define GAS __attribute__((address_space(1)))
; __device__ __forceinline__ v4u pack8(const float (&f)[8]) { v4u w; w.x = pk2(f[0], f[1]); w.y = pk2(f[2], f[3]); w.z = pk2(f[4], f[5]); w.w = pk2(f[6], f[7]); return w; }
; __device__ __forceinline__ float fexp2(float x) { return __builtin_amdgcn_exp2f(x); }
; __device__ __forceinline__ float frcp(float x) { return __builtin_amdgcn_rcpf(x); }
;     __device__ __forceinline__ void operator()(const af4 (&acc)[2][2][4][2], const pg8::Unit& u, int wr_, int wc_, int fr_, int fq_) const {
;     ...
;             for (int m = 0; m < 4; ++m) {
;                 if (ai == 0 && m == 0) load_raw(1);
;                 const int it = wr * 64 + m * 16 + fr;
;                 bf16x8 wf[4];
; #pragma unroll
;                 for (int ks = 0; ks < 4; ++ks) wf[ks] = *(const GAS bf16x8*)(wsg + (size_t)it * 128 + 32 * ks + 8 * fq);
;                 const float bsi = bs[grp * 128 + it];
;                 af4 vm[2] = {(af4){bsi, bsi, bsi, bsi}, (af4){bsi, bsi, bsi, bsi}};
; #pragma unroll
;                 for (int ks = 0; ks < 4; ++ks) {
; #pragma unroll
;                     for (int n = 0; n < 2; ++n) vm[n] = __builtin_amdgcn_mfma_f32_16x16x32_bf16(av[n][ks], wf[ks], vm[n], 0, 0, 0);
;                 }
;                 float o[8];
; #pragma unroll
;                 for (int n = 0; n < 2; ++n)
; #pragma unroll
;                     for (int e = 0; e < 4; e += 2) {
;                         const f32x2 uu = {acc[ai][0][m][n][e], acc[ai][0][m][n][e + 1]}, gg = {acc[ai][1][m][n][e], acc[ai][1][m][n][e + 1]}, vv = {vm[n][e], vm[n][e + 1]};
;                         const f32x2 ar = uu * (uu * uu * (-2.302208198f * 0.044715f) + (-2.302208198f));
;                         const f32x2 gs = gg * (-1.4426950408889634f);
;                         const f32x2 ea = {fexp2(ar.x), fexp2(ar.y)}, eb = {fexp2(gs.x), fexp2(gs.y)};
;                         const f32x2 q = eb + 1.0f, den = ea * q + q;
;                         const f32x2 r = {frcp(den.x), frcp(den.y)};
;                         const f32x2 w = (uu * gg) * vv * r;
;                         o[4 * n + e] = w.x; o[4 * n + e + 1] = w.y; }
;                 *(GAS v4u*)(Y + (size_t)(tok0 + it) * CW + chbase + 32 * wc + 8 * fq) = pack8(o);
	v_mfma_f32_16x16x32_bf16 v[104:107], v[166:169], v[236:239], v[106:109]
	v_mul_f32_e64 v240, v88, v84
	v_mul_f32_e64 v241, v89, v85
	v_pk_mul_f32 v[232:233], v[88:89], v[88:89]
	v_mfma_f32_16x16x32_bf16 v[100:103], v[162:165], v[236:239], v[100:103]
	v_lshl_add_u64 v[108:109], v[228:229], 0, s[40:41]
	v_lshl_add_u64 v[108:109], v[108:109], 0, s[6:7]
	v_lshl_add_u64 v[108:109], v[108:109], 0, v[186:187]
	s_nop 0
	v_pk_mul_f32 v[104:105], v[110:111], v[104:105]
	v_pk_mul_f32 v[106:107], v[112:113], v[106:107]
	s_nop 1
	v_pk_mul_f32 v[100:101], v[252:253], v[100:101]
	v_pk_mul_f32 v[102:103], v[192:193], v[102:103]
	v_pk_mul_f32 v[104:105], v[224:225], v[104:105]
	v_pk_mul_f32 v[106:107], v[226:227], v[106:107]
	v_pk_mul_f32 v[110:111], v[220:221], v[100:101]
	v_pk_mul_f32 v[112:113], v[222:223], v[102:103]
	v_cvt_pk_bf16_f32 v100, v104, v105
	v_cvt_pk_bf16_f32 v101, v106, v107
	v_cvt_pk_bf16_f32 v102, v110, v111
	v_pk_mul_f32 v[106:107], v[90:91], v[90:91]
	v_cvt_pk_bf16_f32 v103, v112, v113
	global_store_dwordx4 v[108:109], v[100:103], off
	global_load_dword v104, v[200:201], off offset:128
	v_pk_mul_f32 v[112:113], v[94:95], s[20:21] op_sel_hi:[1,0]
	v_lshlrev_b64 v[100:101], 8, v[98:99]
	v_lshl_add_u64 v[102:103], v[218:219], 0, v[100:101]
	global_load_dwordx4 v[108:111], v[102:103], off
	global_load_dwordx4 v[220:223], v[102:103], off offset:64
	global_load_dwordx4 v[224:227], v[102:103], off offset:128
	global_load_dwordx4 v[228:231], v[102:103], off offset:192
	v_pk_mul_f32 v[100:101], v[92:93], v[92:93]
	v_pk_mul_f32 v[192:193], v[96:97], s[20:21] op_sel_hi:[1,0]
	v_pk_mul_f32 v[236:237], v[82:83], s[20:21] op_sel_hi:[1,0]
	v_pk_mul_f32 v[238:239], v[86:87], v[82:83]
	v_pk_mul_f32 v[82:83], v[84:85], s[20:21] op_sel_hi:[1,0]
	v_pk_fma_f32 v[84:85], v[106:107], s[16:17], v[196:197] op_sel_hi:[1,0,0] neg_lo:[1,0,0] neg_hi:[1,0,0]
	v_exp_f32_e32 v106, v112
	v_exp_f32_e32 v107, v113
	v_pk_fma_f32 v[100:101], v[100:101], s[16:17], v[196:197] op_sel_hi:[1,0,0] neg_lo:[1,0,0] neg_hi:[1,0,0]
	v_exp_f32_e32 v112, v192
	v_exp_f32_e32 v113, v193
	v_pk_fma_f32 v[192:193], v[234:235], s[16:17], v[196:197] op_sel_hi:[1,0,0] neg_lo:[1,0,0] neg_hi:[1,0,0]
	v_exp_f32_e32 v234, v236
	v_exp_f32_e32 v235, v237
	v_exp_f32_e32 v236, v82
	v_exp_f32_e32 v237, v83
	v_pk_mul_f32 v[82:83], v[90:91], v[84:85]
	v_pk_mul_f32 v[84:85], v[92:93], v[100:101]
	v_pk_mul_f32 v[94:95], v[90:91], v[94:95]
	v_pk_mul_f32 v[96:97], v[92:93], v[96:97]
	v_exp_f32_e32 v90, v82
	v_exp_f32_e32 v91, v83
	v_exp_f32_e32 v92, v84
	v_exp_f32_e32 v93, v85
	v_pk_fma_f32 v[232:233], v[232:233], s[16:17], v[196:197] op_sel_hi:[1,0,0] neg_lo:[1,0,0] neg_hi:[1,0,0]
	v_pk_mul_f32 v[86:87], v[86:87], v[192:193]
	v_pk_mul_f32 v[88:89], v[88:89], v[232:233]
	v_exp_f32_e32 v100, v86
	v_exp_f32_e32 v101, v87
	v_pk_add_f32 v[86:87], v[106:107], 1.0 op_sel_hi:[1,0]
	v_exp_f32_e32 v192, v88
	v_exp_f32_e32 v193, v89
	v_pk_add_f32 v[88:89], v[112:113], 1.0 op_sel_hi:[1,0]
	v_pk_fma_f32 v[90:91], v[90:91], v[86:87], v[86:87]
	v_pk_fma_f32 v[92:93], v[92:93], v[88:89], v[88:89]
	v_pk_add_f32 v[112:113], v[234:235], 1.0 op_sel_hi:[1,0]
	v_pk_add_f32 v[232:233], v[236:237], 1.0 op_sel_hi:[1,0]
	v_pk_fma_f32 v[100:101], v[100:101], v[112:113], v[112:113]
	v_rcp_f32_e32 v90, v90
	v_rcp_f32_e32 v91, v91
	v_rcp_f32_e32 v92, v92
	v_rcp_f32_e32 v93, v93
	v_add_u32_e32 v99, s42, v98
	v_pk_mul_f32 v[112:113], v[78:79], s[20:21] op_sel_hi:[1,0]
	v_pk_mul_f32 v[78:79], v[74:75], v[78:79]
	s_waitcnt vmcnt(4)
	v_mov_b32_e32 v105, v104
	v_mov_b32_e32 v106, v104
	v_mov_b32_e32 v107, v104
	s_waitcnt vmcnt(3)
	s_nop 0
	v_mfma_f32_16x16x32_bf16 v[82:85], v[130:133], v[108:111], v[104:107]
	v_mfma_f32_16x16x32_bf16 v[86:89], v[134:137], v[108:111], v[104:107]
	v_mad_i64_i32 v[108:109], s[26:27], v99, s61, v[198:199]
	v_lshl_add_u64 v[108:109], v[108:109], 0, s[40:41]
	s_waitcnt vmcnt(2)
	v_mfma_f32_16x16x32_bf16 v[82:85], v[142:145], v[220:223], v[82:85]
	v_fma_f32 v104, v192, v232, v232
	v_fma_f32 v105, v193, v233, v233
	v_rcp_f32_e32 v106, v100
	v_rcp_f32_e32 v107, v101
	v_mfma_f32_16x16x32_bf16 v[86:89], v[138:141], v[220:223], v[86:89]
	v_rcp_f32_e32 v104, v104
	v_rcp_f32_e32 v105, v105
	v_lshl_add_u64 v[108:109], v[108:109], 0, s[6:7]
	s_waitcnt vmcnt(1)
	v_mfma_f32_16x16x32_bf16 v[82:85], v[150:153], v[224:227], v[82:85]
	v_lshl_add_u64 v[108:109], v[108:109], 0, v[186:187]
	v_or_b32_e32 v100, 48, v210
	v_ashrrev_i32_e32 v101, 31, v100
	v_mfma_f32_16x16x32_bf16 v[86:89], v[146:149], v[224:227], v[86:89]
	v_mul_f32_e64 v110, v74, v74
	v_mul_f32_e64 v111, v75, v75
	v_pk_mul_f32 v[192:193], v[80:81], s[20:21] op_sel_hi:[1,0]
	v_pk_mul_f32 v[220:221], v[70:71], v[70:71]
	s_waitcnt vmcnt(0)
;     __device__ __forceinline__ void operator()(const af4 (&acc)[2][2][4][2], const pg8::Unit& u, int wr_, int wc_, int fr_, int fq_) const {
;     ...
;             for (int ks = 0; ks < 4; ++ks) {
;                 const int j0 = tok0 + 32 * ks + 8 * fq;
;                 f32x4 st[4];
; #pragma unroll
;                 for (int q = 0; q < 4; ++q) st[q] = *(const GAS f32x4*)(stats + (size_t)(j0 + 2 * q) * 2);
; #pragma unroll
;                 for (int n = 0; n < 2; ++n) {
;                     float vf[8];
;                     unpack8(raw[n][ks], vf);
; #pragma unroll
;                     for (int q = 0; q < 4; ++q) { f32x2 t = {vf[2 * q], vf[2 * q + 1]}; t = t * (f32x2){st[q].z, st[q].w} + (f32x2){st[q].x, st[q].y}; t = t * lg[n] + lb[n]; vf[2 * q] = t.x; vf[2 * q + 1] = t.y; }
;                     av[n][ks] = __builtin_bit_cast(bf16x8, pack8(vf));
;                 }
;             }
; #pragma unroll
;             for (int m = 0; m < 4; ++m) {
;                 if (ai == 0 && m == 0) load_raw(1);
;                 const int it = wr * 64 + m * 16 + fr;
;                 bf16x8 wf[4];
; #pragma unroll
;                 for (int ks = 0; ks < 4; ++ks) wf[ks] = *(const GAS bf16x8*)(wsg + (size_t)it * 128 + 32 * ks + 8 * fq);
;                 const float bsi = bs[grp * 128 + it];
;                 af4 vm[2] = {(af4){bsi, bsi, bsi, bsi}, (af4){bsi, bsi, bsi, bsi}};
; #pragma unroll
;                 for (int ks = 0; ks < 4; ++ks) {
; #pragma unroll
;                     for (int n = 0; n < 2; ++n) vm[n] = __builtin_amdgcn_mfma_f32_16x16x32_bf16(av[n][ks], wf[ks], vm[n], 0, 0, 0);
;                 }
;                 float o[8];
; #pragma unroll
;                 for (int n = 0; n < 2; ++n)
; #pragma unroll
;                     for (int e = 0; e < 4; e += 2) {
;                         const f32x2 uu = {acc[ai][0][m][n][e], acc[ai][0][m][n][e + 1]}, gg = {acc[ai][1][m][n][e], acc[ai][1][m][n][e + 1]}, vv = {vm[n][e], vm[n][e + 1]};
;                         const f32x2 ar = uu * (uu * uu * (-2.302208198f * 0.044715f) + (-2.302208198f));
;                         const f32x2 gs = gg * (-1.4426950408889634f);
;                         const f32x2 ea = {fexp2(ar.x), fexp2(ar.y)}, eb = {fexp2(gs.x), fexp2(gs.y)};
;                         const f32x2 q = eb + 1.0f, den = ea * q + q;
;                         const f32x2 r = {frcp(den.x), frcp(den.y)};
	v_mfma_f32_16x16x32_bf16 v[82:85], v[166:169], v[228:231], v[82:85]
	v_mul_f32_e64 v222, v66, s20
	v_mul_f32_e64 v223, v67, s20
	v_pk_mul_f32 v[224:225], v[70:71], v[66:67]
	v_pk_mul_f32 v[66:67], v[68:69], s[20:21] op_sel_hi:[1,0]
	v_mfma_f32_16x16x32_bf16 v[86:89], v[162:165], v[228:231], v[86:89]
	v_mul_f32_e64 v226, v72, v68
	v_mul_f32_e64 v227, v73, v69
	s_nop 0
	v_pk_mul_f32 v[82:83], v[94:95], v[82:83]
	v_pk_mul_f32 v[84:85], v[96:97], v[84:85]
	v_pk_mul_f32 v[82:83], v[90:91], v[82:83]
	v_pk_mul_f32 v[84:85], v[92:93], v[84:85]
	s_nop 0
	v_pk_mul_f32 v[86:87], v[238:239], v[86:87]
	v_pk_mul_f32 v[88:89], v[240:241], v[88:89]
	v_pk_mul_f32 v[86:87], v[106:107], v[86:87]
	v_pk_mul_f32 v[88:89], v[104:105], v[88:89]
	v_cvt_pk_bf16_f32 v82, v82, v83
	v_cvt_pk_bf16_f32 v83, v84, v85
	v_cvt_pk_bf16_f32 v84, v86, v87
	v_pk_fma_f32 v[68:69], v[110:111], s[16:17], v[196:197] op_sel_hi:[1,0,0] neg_lo:[1,0,0] neg_hi:[1,0,0]
	v_cvt_pk_bf16_f32 v85, v88, v89
	global_store_dwordx4 v[108:109], v[82:85], off
	global_load_dword v82, v[200:201], off offset:192
	v_exp_f32_e32 v110, v112
	v_lshlrev_b64 v[84:85], 8, v[100:101]
	v_lshl_add_u64 v[104:105], v[218:219], 0, v[84:85]
	global_load_dwordx4 v[86:89], v[104:105], off
	global_load_dwordx4 v[90:93], v[104:105], off offset:64
	global_load_dwordx4 v[94:97], v[104:105], off offset:128
	global_load_dwordx4 v[106:109], v[104:105], off offset:192
	v_pk_mul_f32 v[84:85], v[76:77], v[76:77]
	v_pk_mul_f32 v[218:219], v[72:73], v[72:73]
	v_exp_f32_e32 v111, v113
	v_pk_fma_f32 v[84:85], v[84:85], s[16:17], v[196:197] op_sel_hi:[1,0,0] neg_lo:[1,0,0] neg_hi:[1,0,0]
	v_exp_f32_e32 v112, v192
	v_exp_f32_e32 v113, v193
	v_pk_fma_f32 v[192:193], v[220:221], s[16:17], v[196:197] op_sel_hi:[1,0,0] neg_lo:[1,0,0] neg_hi:[1,0,0]
	v_pk_fma_f32 v[218:219], v[218:219], s[16:17], v[196:197] op_sel_hi:[1,0,0] neg_lo:[1,0,0] neg_hi:[1,0,0]
	v_pk_mul_f32 v[68:69], v[74:75], v[68:69]
	v_exp_f32_e32 v220, v222
	v_exp_f32_e32 v221, v223
	v_exp_f32_e32 v66, v66
	v_exp_f32_e32 v67, v67
	v_pk_mul_f32 v[74:75], v[76:77], v[84:85]
	v_pk_mul_f32 v[70:71], v[70:71], v[192:193]
	v_pk_mul_f32 v[72:73], v[72:73], v[218:219]
	v_exp_f32_e32 v68, v68
	v_exp_f32_e32 v69, v69
	v_exp_f32_e32 v74, v74
	v_exp_f32_e32 v75, v75
	v_exp_f32_e32 v70, v70
	v_exp_f32_e32 v71, v71
	v_exp_f32_e32 v72, v72
	v_exp_f32_e32 v73, v73
	v_pk_mul_f32 v[80:81], v[76:77], v[80:81]
	v_pk_add_f32 v[76:77], v[110:111], 1.0 op_sel_hi:[1,0]
	v_pk_add_f32 v[110:111], v[112:113], 1.0 op_sel_hi:[1,0]
	v_pk_add_f32 v[112:113], v[220:221], 1.0 op_sel_hi:[1,0]
	v_pk_add_f32 v[192:193], v[66:67], 1.0 op_sel_hi:[1,0]
	v_pk_fma_f32 v[76:77], v[68:69], v[76:77], v[76:77]
	v_pk_fma_f32 v[74:75], v[74:75], v[110:111], v[110:111]
	v_pk_fma_f32 v[110:111], v[70:71], v[112:113], v[112:113]
	v_pk_fma_f32 v[112:113], v[72:73], v[192:193], v[192:193]
	v_rcp_f32_e32 v76, v76
	v_rcp_f32_e32 v77, v77
	v_rcp_f32_e32 v74, v74
	v_rcp_f32_e32 v75, v75
	v_add_u32_e32 v99, s23, v210
	s_waitcnt vmcnt(4)
	v_mov_b32_e32 v83, v82
	v_mov_b32_e32 v84, v82
	v_mov_b32_e32 v85, v82
	s_waitcnt vmcnt(3)
	s_nop 0
	v_mfma_f32_16x16x32_bf16 v[66:69], v[130:133], v[86:89], v[82:85]
	v_lshlrev_b32_e32 v130, 16, v156
	v_and_b32_e32 v131, 0xffff0000, v156
	v_lshlrev_b32_e32 v132, 16, v157
	v_mfma_f32_16x16x32_bf16 v[70:73], v[134:137], v[86:89], v[82:85]
	v_rcp_f32_e32 v86, v112
	v_rcp_f32_e32 v87, v113
	v_lshlrev_b32_e32 v112, 16, v155
	s_waitcnt vmcnt(2)
	v_mfma_f32_16x16x32_bf16 v[66:69], v[142:145], v[90:93], v[66:69]
	v_rcp_f32_e32 v84, v110
	v_rcp_f32_e32 v85, v111
	v_or_b32_e32 v82, s23, v209
	v_mfma_f32_16x16x32_bf16 v[70:73], v[138:141], v[90:93], v[70:73]
	v_add_u32_e32 v90, s42, v100
	v_mad_i64_i32 v[90:91], s[26:27], v90, s61, v[198:199]
	s_waitcnt vmcnt(1)
	v_mfma_f32_16x16x32_bf16 v[66:69], v[150:153], v[94:97], v[66:69]
	v_lshl_add_u64 v[90:91], v[90:91], 0, s[40:41]
	v_lshl_add_u64 v[90:91], v[90:91], 0, s[6:7]
	v_ashrrev_i32_e32 v83, 31, v82
	v_mfma_f32_16x16x32_bf16 v[70:73], v[146:149], v[94:97], v[70:73]
	v_lshl_add_u64 v[90:91], v[90:91], 0, v[186:187]
	v_lshl_add_u32 v88, v82, 3, s98
	v_lshlrev_b32_e32 v92, 16, v177
	s_waitcnt vmcnt(0)
	v_mfma_f32_16x16x32_bf16 v[66:69], v[166:169], v[106:109], v[66:69]
	v_and_b32_e32 v93, 0xffff0000, v177
	v_lshlrev_b32_e32 v94, 16, v170
	v_and_b32_e32 v95, 0xffff0000, v170
	v_mfma_f32_16x16x32_bf16 v[70:73], v[162:165], v[106:109], v[70:73]
	v_lshlrev_b32_e32 v96, 16, v171
	s_nop 2
	v_pk_mul_f32 v[66:67], v[78:79], v[66:67]
	v_pk_mul_f32 v[68:69], v[80:81], v[68:69]
	v_pk_mul_f32 v[66:67], v[76:77], v[66:67]
	v_pk_mul_f32 v[68:69], v[74:75], v[68:69]
	v_pk_mul_f32 v[70:71], v[224:225], v[70:71]
	v_pk_mul_f32 v[72:73], v[226:227], v[72:73]
	v_pk_mul_f32 v[70:71], v[84:85], v[70:71]
	v_pk_mul_f32 v[72:73], v[86:87], v[72:73]
	v_cvt_pk_bf16_f32 v66, v66, v67
	v_cvt_pk_bf16_f32 v67, v68, v69
	v_cvt_pk_bf16_f32 v68, v70, v71
	v_or_b32_e32 v84, 32, v82
	v_cvt_pk_bf16_f32 v69, v72, v73
	global_store_dwordx4 v[90:91], v[66:69], off
	ds_read_b128 v[66:69], v88
	s_nop 0
	ds_read_b128 v[70:73], v88 offset:16
	ds_read_b128 v[74:77], v88 offset:32
	ds_read_b128 v[78:81], v88 offset:48
	v_ashrrev_i32_e32 v85, 31, v84
	v_lshl_add_u32 v88, v84, 3, s98
	v_lshlrev_b32_e32 v84, 16, v174
	v_and_b32_e32 v85, 0xffff0000, v174
	v_lshlrev_b32_e32 v86, 16, v175
	v_and_b32_e32 v87, 0xffff0000, v175
	v_lshlrev_b32_e32 v90, 16, v176
	v_and_b32_e32 v91, 0xffff0000, v176
	v_and_b32_e32 v97, 0xffff0000, v171
	v_lshlrev_b32_e32 v106, 16, v172
	v_and_b32_e32 v107, 0xffff0000, v172
	v_lshlrev_b32_e32 v108, 16, v173
	v_and_b32_e32 v109, 0xffff0000, v173
	v_lshlrev_b32_e32 v110, 16, v154
	v_and_b32_e32 v111, 0xffff0000, v154
	v_and_b32_e32 v113, 0xffff0000, v155
	v_and_b32_e32 v133, 0xffff0000, v157
	v_pk_mul_f32 v[134:135], v[54:55], v[54:55]
	v_pk_mul_f32 v[136:137], v[50:51], s[20:21] op_sel_hi:[1,0]
	v_pk_mul_f32 v[138:139], v[54:55], v[50:51]
	v_pk_mul_f32 v[50:51], v[52:53], s[20:21] op_sel_hi:[1,0]
	v_pk_mul_f32 v[140:141], v[56:57], v[52:53]
	s_waitcnt lgkmcnt(3)
; #define GAS __attribute__((address_space(1)))
; __device__ __forceinline__ void unpack8(const v4u w, float (&f)[8]) { f[0] = bflo(w.x); f[1] = bfhi(w.x); f[2] = bflo(w.y); f[3] = bfhi(w.y); f[4] = bflo(w.z); f[5] = bfhi(w.z); f[6] = bflo(w.w); f[7] = bfhi(w.w); }
; __device__ __forceinline__ v4u pack8(const float (&f)[8]) { v4u w; w.x = pk2(f[0], f[1]); w.y = pk2(f[2], f[3]); w.z = pk2(f[4], f[5]); w.w = pk2(f[6], f[7]); return w; }
;     __device__ __forceinline__ void operator()(const af4 (&acc)[2][2][4][2], const pg8::Unit& u, int wr_, int wc_, int fr_, int fq_) const {
;     ...
;             for (int ks = 0; ks < 4; ++ks) {
;                 const int j0 = tok0 + 32 * ks + 8 * fq;
;                 f32x4 st[4];
; #pragma unroll
;                 for (int q = 0; q < 4; ++q) st[q] = *(const GAS f32x4*)(stats + (size_t)(j0 + 2 * q) * 2);
; #pragma unroll
;                 for (int n = 0; n < 2; ++n) {
;                     float vf[8];
;                     unpack8(raw[n][ks], vf);
; #pragma unroll
;                     for (int q = 0; q < 4; ++q) { f32x2 t = {vf[2 * q], vf[2 * q + 1]}; t = t * (f32x2){st[q].z, st[q].w} + (f32x2){st[q].x, st[q].y}; t = t * lg[n] + lb[n]; vf[2 * q] = t.x; vf[2 * q + 1] = t.y; }
;                     av[n][ks] = __builtin_bit_cast(bf16x8, pack8(vf));
;                 }
	v_pk_fma_f32 v[84:85], v[68:69], v[84:85], v[66:67]
	s_waitcnt lgkmcnt(2)
	v_pk_fma_f32 v[86:87], v[72:73], v[86:87], v[70:71]
	s_waitcnt lgkmcnt(1)
	v_pk_fma_f32 v[90:91], v[76:77], v[90:91], v[74:75]
	s_waitcnt lgkmcnt(0)
	v_pk_fma_f32 v[92:93], v[80:81], v[92:93], v[78:79]
	v_pk_fma_f32 v[66:67], v[68:69], v[94:95], v[66:67]
	v_pk_fma_f32 v[68:69], v[72:73], v[96:97], v[70:71]
	v_pk_fma_f32 v[70:71], v[76:77], v[106:107], v[74:75]
	v_pk_fma_f32 v[72:73], v[80:81], v[108:109], v[78:79]
	v_pk_fma_f32 v[74:75], v[208:209], v[84:85], v[206:207] op_sel_hi:[0,1,0]
	v_pk_fma_f32 v[76:77], v[208:209], v[86:87], v[206:207] op_sel_hi:[0,1,0]
	v_pk_fma_f32 v[78:79], v[208:209], v[90:91], v[206:207] op_sel_hi:[0,1,0]
	v_pk_fma_f32 v[80:81], v[208:209], v[92:93], v[206:207] op_sel_hi:[0,1,0]
	v_pk_fma_f32 v[66:67], v[202:203], v[66:67], v[204:205] op_sel_hi:[0,1,0]
	v_pk_fma_f32 v[68:69], v[202:203], v[68:69], v[204:205] op_sel_hi:[0,1,0]
	v_pk_fma_f32 v[84:85], v[202:203], v[70:71], v[204:205] op_sel_hi:[0,1,0]
	v_pk_fma_f32 v[86:87], v[202:203], v[72:73], v[204:205] op_sel_hi:[0,1,0]
	v_cvt_pk_bf16_f32 v70, v74, v75
	v_cvt_pk_bf16_f32 v71, v76, v77
	v_cvt_pk_bf16_f32 v72, v78, v79
	v_cvt_pk_bf16_f32 v73, v80, v81
	v_cvt_pk_bf16_f32 v66, v66, v67
	v_cvt_pk_bf16_f32 v67, v68, v69
	v_cvt_pk_bf16_f32 v68, v84, v85
	v_cvt_pk_bf16_f32 v69, v86, v87
	ds_read_b128 v[74:77], v88
	ds_read_b128 v[78:81], v88 offset:16
	ds_read_b128 v[84:87], v88 offset:32
	s_nop 0
	ds_read_b128 v[88:91], v88 offset:48
	v_or_b32_e32 v92, 64, v82
	v_ashrrev_i32_e32 v93, 31, v92
	v_lshl_add_u32 v96, v92, 3, s98
	v_lshlrev_b32_e32 v92, 16, v158
	v_and_b32_e32 v93, 0xffff0000, v158
	v_lshlrev_b32_e32 v94, 16, v159
	v_and_b32_e32 v95, 0xffff0000, v159
	v_lshlrev_b32_e32 v106, 16, v160
	v_and_b32_e32 v107, 0xffff0000, v160
	v_lshlrev_b32_e32 v108, 16, v161
	v_and_b32_e32 v109, 0xffff0000, v161
	v_or_b32_e32 v82, 0x60, v82
	v_ashrrev_i32_e32 v83, 31, v82
	s_waitcnt lgkmcnt(3)
	v_pk_fma_f32 v[92:93], v[76:77], v[92:93], v[74:75]
	s_waitcnt lgkmcnt(2)
	v_pk_fma_f32 v[94:95], v[80:81], v[94:95], v[78:79]
	s_waitcnt lgkmcnt(1)
	v_pk_fma_f32 v[106:107], v[86:87], v[106:107], v[84:85]
	s_waitcnt lgkmcnt(0)
	v_pk_fma_f32 v[108:109], v[90:91], v[108:109], v[88:89]
	v_pk_fma_f32 v[74:75], v[76:77], v[110:111], v[74:75]
	v_pk_fma_f32 v[76:77], v[80:81], v[112:113], v[78:79]
	v_pk_fma_f32 v[78:79], v[86:87], v[130:131], v[84:85]
	v_pk_fma_f32 v[80:81], v[90:91], v[132:133], v[88:89]
	v_pk_fma_f32 v[84:85], v[208:209], v[92:93], v[206:207] op_sel_hi:[0,1,0]
	v_pk_fma_f32 v[86:87], v[208:209], v[94:95], v[206:207] op_sel_hi:[0,1,0]
	v_pk_fma_f32 v[88:89], v[208:209], v[106:107], v[206:207] op_sel_hi:[0,1,0]
	v_pk_fma_f32 v[90:91], v[208:209], v[108:109], v[206:207] op_sel_hi:[0,1,0]
	v_pk_fma_f32 v[74:75], v[202:203], v[74:75], v[204:205] op_sel_hi:[0,1,0]
	v_pk_fma_f32 v[76:77], v[202:203], v[76:77], v[204:205] op_sel_hi:[0,1,0]
	v_pk_fma_f32 v[92:93], v[202:203], v[78:79], v[204:205] op_sel_hi:[0,1,0]
	v_pk_fma_f32 v[94:95], v[202:203], v[80:81], v[204:205] op_sel_hi:[0,1,0]
	v_cvt_pk_bf16_f32 v78, v84, v85
	v_cvt_pk_bf16_f32 v79, v86, v87
	v_cvt_pk_bf16_f32 v80, v88, v89
	v_cvt_pk_bf16_f32 v81, v90, v91
	v_cvt_pk_bf16_f32 v74, v74, v75
	v_cvt_pk_bf16_f32 v75, v76, v77
	v_cvt_pk_bf16_f32 v76, v92, v93
	v_cvt_pk_bf16_f32 v77, v94, v95
	ds_read_b128 v[84:87], v96
	ds_read_b128 v[88:91], v96 offset:16
	ds_read_b128 v[92:95], v96 offset:32
	ds_read_b128 v[106:109], v96 offset:48
	v_lshl_add_u32 v110, v82, 3, s98
	v_lshlrev_b32_e32 v82, 16, v126
	v_and_b32_e32 v83, 0xffff0000, v126
	v_lshlrev_b32_e32 v96, 16, v127
	v_and_b32_e32 v97, 0xffff0000, v127
	v_lshlrev_b32_e32 v112, 16, v128
	v_and_b32_e32 v113, 0xffff0000, v128
	v_lshlrev_b32_e32 v126, 16, v129
	v_and_b32_e32 v127, 0xffff0000, v129
	v_lshlrev_b32_e32 v128, 16, v122
	v_and_b32_e32 v129, 0xffff0000, v122
	v_lshlrev_b32_e32 v122, 16, v123
	v_and_b32_e32 v123, 0xffff0000, v123
	v_lshlrev_b32_e32 v130, 16, v124
	v_and_b32_e32 v131, 0xffff0000, v124
	v_lshlrev_b32_e32 v124, 16, v125
	v_and_b32_e32 v125, 0xffff0000, v125
	v_pk_mul_f32 v[132:133], v[56:57], v[56:57]
	s_waitcnt lgkmcnt(3)
	v_pk_fma_f32 v[82:83], v[86:87], v[82:83], v[84:85]
	s_waitcnt lgkmcnt(2)
	v_pk_fma_f32 v[96:97], v[90:91], v[96:97], v[88:89]
	s_waitcnt lgkmcnt(1)
	v_pk_fma_f32 v[112:113], v[94:95], v[112:113], v[92:93]
	s_waitcnt lgkmcnt(0)
	v_pk_fma_f32 v[126:127], v[108:109], v[126:127], v[106:107]
	v_pk_fma_f32 v[84:85], v[86:87], v[128:129], v[84:85]
	v_pk_fma_f32 v[86:87], v[90:91], v[122:123], v[88:89]
	v_pk_fma_f32 v[88:89], v[94:95], v[130:131], v[92:93]
	v_pk_fma_f32 v[90:91], v[108:109], v[124:125], v[106:107]
	v_pk_fma_f32 v[82:83], v[208:209], v[82:83], v[206:207] op_sel_hi:[0,1,0]
	v_pk_fma_f32 v[92:93], v[208:209], v[96:97], v[206:207] op_sel_hi:[0,1,0]
	v_pk_fma_f32 v[94:95], v[208:209], v[112:113], v[206:207] op_sel_hi:[0,1,0]
	v_pk_fma_f32 v[96:97], v[208:209], v[126:127], v[206:207] op_sel_hi:[0,1,0]
	v_pk_fma_f32 v[84:85], v[202:203], v[84:85], v[204:205] op_sel_hi:[0,1,0]
	v_pk_fma_f32 v[106:107], v[202:203], v[86:87], v[204:205] op_sel_hi:[0,1,0]
	v_pk_fma_f32 v[108:109], v[202:203], v[88:89], v[204:205] op_sel_hi:[0,1,0]
	v_pk_fma_f32 v[90:91], v[202:203], v[90:91], v[204:205] op_sel_hi:[0,1,0]
	v_cvt_pk_bf16_f32 v86, v82, v83
	v_cvt_pk_bf16_f32 v87, v92, v93
	v_cvt_pk_bf16_f32 v88, v94, v95
	v_cvt_pk_bf16_f32 v89, v96, v97
	v_cvt_pk_bf16_f32 v82, v84, v85
	v_cvt_pk_bf16_f32 v83, v106, v107
	v_cvt_pk_bf16_f32 v84, v108, v109
	v_cvt_pk_bf16_f32 v85, v90, v91
	ds_read_b128 v[90:93], v110
	ds_read_b128 v[94:97], v110 offset:16
	ds_read_b128 v[106:109], v110 offset:32
	s_nop 0
	ds_read_b128 v[110:113], v110 offset:48
	v_lshlrev_b32_e32 v122, 16, v118
	v_and_b32_e32 v123, 0xffff0000, v118
	v_lshlrev_b32_e32 v118, 16, v119
	v_and_b32_e32 v119, 0xffff0000, v119
	v_lshlrev_b32_e32 v124, 16, v120
	v_and_b32_e32 v125, 0xffff0000, v120
	v_lshlrev_b32_e32 v120, 16, v121
	v_and_b32_e32 v121, 0xffff0000, v121
	v_lshlrev_b32_e32 v126, 16, v114
	v_and_b32_e32 v127, 0xffff0000, v114
	v_lshlrev_b32_e32 v114, 16, v115
	v_and_b32_e32 v115, 0xffff0000, v115
	v_lshlrev_b32_e32 v128, 16, v116
	v_and_b32_e32 v129, 0xffff0000, v116
	v_lshlrev_b32_e32 v116, 16, v117
	v_and_b32_e32 v117, 0xffff0000, v117
	v_pk_mul_f32 v[130:131], v[64:65], s[20:21] op_sel_hi:[1,0]
	v_pk_fma_f32 v[132:133], v[132:133], s[16:17], v[196:197] op_sel_hi:[1,0,0] neg_lo:[1,0,0] neg_hi:[1,0,0]
	v_pk_mul_f32 v[64:65], v[60:61], v[64:65]
	v_pk_mul_f32 v[56:57], v[56:57], v[132:133]
	s_waitcnt lgkmcnt(3)
; #define GAS __attribute__((address_space(1)))
; __device__ __forceinline__ float fexp2(float x) { return __builtin_amdgcn_exp2f(x); }
;     __device__ __forceinline__ void operator()(const af4 (&acc)[2][2][4][2], const pg8::Unit& u, int wr_, int wc_, int fr_, int fq_) const {
;     ...
;                     unpack8(raw[n][ks], vf);
; #pragma unroll
;                     for (int q = 0; q < 4; ++q) { f32x2 t = {vf[2 * q], vf[2 * q + 1]}; t = t * (f32x2){st[q].z, st[q].w} + (f32x2){st[q].x, st[q].y}; t = t * lg[n] + lb[n]; vf[2 * q] = t.x; vf[2 * q + 1] = t.y; }
;                     av[n][ks] = __builtin_bit_cast(bf16x8, pack8(vf));
;                 }
;             }
; #pragma unroll
;             for (int m = 0; m < 4; ++m) {
;                 if (ai == 0 && m == 0) load_raw(1);
;                 const int it = wr * 64 + m * 16 + fr;
;                 bf16x8 wf[4];
; #pragma unroll
;                 for (int ks = 0; ks < 4; ++ks) wf[ks] = *(const GAS bf16x8*)(wsg + (size_t)it * 128 + 32 * ks + 8 * fq);
;                 const float bsi = bs[grp * 128 + it];
;                 af4 vm[2] = {(af4){bsi, bsi, bsi, bsi}, (af4){bsi, bsi, bsi, bsi}};
; #pragma unroll
;                 for (int ks = 0; ks < 4; ++ks) {
; #pragma unroll
;                     for (int n = 0; n < 2; ++n) vm[n] = __builtin_amdgcn_mfma_f32_16x16x32_bf16(av[n][ks], wf[ks], vm[n], 0, 0, 0);
;                 }
;                 float o[8];
; #pragma unroll
;                 for (int n = 0; n < 2; ++n)
; #pragma unroll
;                     for (int e = 0; e < 4; e += 2) {
;                         const f32x2 uu = {acc[ai][0][m][n][e], acc[ai][0][m][n][e + 1]}, gg = {acc[ai][1][m][n][e], acc[ai][1][m][n][e + 1]}, vv = {vm[n][e], vm[n][e + 1]};
;                         const f32x2 ar = uu * (uu * uu * (-2.302208198f * 0.044715f) + (-2.302208198f));
;                         const f32x2 gs = gg * (-1.4426950408889634f);
;                         const f32x2 ea = {fexp2(ar.x), fexp2(ar.y)}, eb = {fexp2(gs.x), fexp2(gs.y)};
;                         const f32x2 q = eb + 1.0f, den = ea * q + q;
;                         const f32x2 r = {frcp(den.x), frcp(den.y)};
;                         const f32x2 w = (uu * gg) * vv * r;
;                         o[4 * n + e] = w.x; o[4 * n + e + 1] = w.y; }
;                 *(GAS v4u*)(Y + (size_t)(tok0 + it) * CW + chbase + 32 * wc + 8 * fq) = pack8(o);
	v_pk_fma_f32 v[122:123], v[92:93], v[122:123], v[90:91]
	s_waitcnt lgkmcnt(2)
	v_pk_fma_f32 v[118:119], v[96:97], v[118:119], v[94:95]
	s_waitcnt lgkmcnt(1)
	v_pk_fma_f32 v[124:125], v[108:109], v[124:125], v[106:107]
	s_waitcnt lgkmcnt(0)
	v_pk_fma_f32 v[120:121], v[112:113], v[120:121], v[110:111]
	v_pk_fma_f32 v[90:91], v[92:93], v[126:127], v[90:91]
	v_pk_fma_f32 v[92:93], v[96:97], v[114:115], v[94:95]
	v_pk_fma_f32 v[94:95], v[108:109], v[128:129], v[106:107]
	v_pk_fma_f32 v[96:97], v[112:113], v[116:117], v[110:111]
	v_pk_fma_f32 v[106:107], v[208:209], v[122:123], v[206:207] op_sel_hi:[0,1,0]
	v_pk_fma_f32 v[108:109], v[208:209], v[118:119], v[206:207] op_sel_hi:[0,1,0]
	v_pk_fma_f32 v[110:111], v[208:209], v[124:125], v[206:207] op_sel_hi:[0,1,0]
	v_pk_fma_f32 v[112:113], v[208:209], v[120:121], v[206:207] op_sel_hi:[0,1,0]
	v_pk_fma_f32 v[114:115], v[202:203], v[90:91], v[204:205] op_sel_hi:[0,1,0]
	v_pk_fma_f32 v[116:117], v[202:203], v[92:93], v[204:205] op_sel_hi:[0,1,0]
	v_pk_fma_f32 v[118:119], v[202:203], v[94:95], v[204:205] op_sel_hi:[0,1,0]
	v_pk_fma_f32 v[120:121], v[202:203], v[96:97], v[204:205] op_sel_hi:[0,1,0]
	v_cvt_pk_bf16_f32 v90, v106, v107
	v_cvt_pk_bf16_f32 v91, v108, v109
	v_cvt_pk_bf16_f32 v92, v110, v111
	v_cvt_pk_bf16_f32 v93, v112, v113
	v_cvt_pk_bf16_f32 v94, v114, v115
	v_cvt_pk_bf16_f32 v95, v116, v117
	v_cvt_pk_bf16_f32 v96, v118, v119
	v_cvt_pk_bf16_f32 v97, v120, v121
	global_load_dword v106, v[200:201], off
	global_load_dwordx4 v[110:113], v[214:215], off
	global_load_dwordx4 v[114:117], v[214:215], off offset:64
	global_load_dwordx4 v[118:121], v[214:215], off offset:128
	global_load_dwordx4 v[122:125], v[214:215], off offset:192
	v_pk_mul_f32 v[108:109], v[60:61], v[60:61]
	v_pk_mul_f32 v[126:127], v[58:59], v[58:59]
	v_pk_mul_f32 v[128:129], v[62:63], s[20:21] op_sel_hi:[1,0]
	v_pk_fma_f32 v[52:53], v[126:127], s[16:17], v[196:197] op_sel_hi:[1,0,0] neg_lo:[1,0,0] neg_hi:[1,0,0]
	v_pk_fma_f32 v[108:109], v[108:109], s[16:17], v[196:197] op_sel_hi:[1,0,0] neg_lo:[1,0,0] neg_hi:[1,0,0]
	v_exp_f32_e32 v126, v128
	v_exp_f32_e32 v127, v129
	v_exp_f32_e32 v128, v130
	v_exp_f32_e32 v129, v131
	v_pk_fma_f32 v[130:131], v[134:135], s[16:17], v[196:197] op_sel_hi:[1,0,0] neg_lo:[1,0,0] neg_hi:[1,0,0]
	v_exp_f32_e32 v134, v136
	v_exp_f32_e32 v135, v137
	v_exp_f32_e32 v136, v50
	v_exp_f32_e32 v137, v51
	v_pk_mul_f32 v[50:51], v[58:59], v[52:53]
	v_pk_mul_f32 v[52:53], v[60:61], v[108:109]
	v_pk_mul_f32 v[62:63], v[58:59], v[62:63]
	v_pk_mul_f32 v[54:55], v[54:55], v[130:131]
	v_exp_f32_e32 v58, v50
	v_exp_f32_e32 v59, v51
	v_exp_f32_e32 v60, v52
	v_exp_f32_e32 v61, v53
	v_exp_f32_e32 v130, v54
	v_exp_f32_e32 v131, v55
	v_exp_f32_e32 v132, v56
	v_exp_f32_e32 v133, v57
	v_pk_add_f32 v[126:127], v[126:127], 1.0 op_sel_hi:[1,0]
	v_pk_add_f32 v[128:129], v[128:129], 1.0 op_sel_hi:[1,0]
	v_pk_add_f32 v[134:135], v[134:135], 1.0 op_sel_hi:[1,0]
	v_pk_add_f32 v[136:137], v[136:137], 1.0 op_sel_hi:[1,0]
	v_pk_fma_f32 v[58:59], v[58:59], v[126:127], v[126:127]
	v_pk_fma_f32 v[60:61], v[60:61], v[128:129], v[128:129]
	v_rcp_f32_e32 v58, v58
	v_rcp_f32_e32 v59, v59
	v_rcp_f32_e32 v60, v60
	v_rcp_f32_e32 v61, v61
	s_waitcnt vmcnt(4)
	v_mov_b32_e32 v107, v106
	v_mov_b32_e32 v108, v106
	v_mov_b32_e32 v109, v106
	s_waitcnt vmcnt(3)
	s_nop 0
	v_mfma_f32_16x16x32_bf16 v[50:53], v[70:73], v[110:113], v[106:109]
	v_mfma_f32_16x16x32_bf16 v[54:57], v[66:69], v[110:113], v[106:109]
	v_mad_i64_i32 v[110:111], s[26:27], v99, s61, v[198:199]
	v_lshl_add_u64 v[110:111], v[110:111], 0, s[40:41]
	s_waitcnt vmcnt(2)
	v_mfma_f32_16x16x32_bf16 v[50:53], v[78:81], v[114:117], v[50:53]
	v_fma_f32 v106, v130, v134, v134
	v_fma_f32 v107, v131, v135, v135
	v_pk_fma_f32 v[108:109], v[132:133], v[136:137], v[136:137]
	v_rcp_f32_e32 v106, v106
	v_mfma_f32_16x16x32_bf16 v[54:57], v[74:77], v[114:117], v[54:57]
	v_rcp_f32_e32 v107, v107
	v_rcp_f32_e32 v108, v108
	v_rcp_f32_e32 v109, v109
	s_waitcnt vmcnt(1)
	v_mfma_f32_16x16x32_bf16 v[50:53], v[86:89], v[118:121], v[50:53]
	v_lshl_add_u64 v[110:111], v[110:111], 0, s[6:7]
	v_lshl_add_u64 v[110:111], v[110:111], 0, v[186:187]
	v_pk_mul_f32 v[112:113], v[46:47], s[20:21] op_sel_hi:[1,0]
	v_mfma_f32_16x16x32_bf16 v[54:57], v[82:85], v[118:121], v[54:57]
	v_mul_f32_e64 v114, v48, s20
	v_mul_f32_e64 v115, v49, s20
	v_pk_mul_f32 v[116:117], v[40:41], v[40:41]
	v_pk_mul_f32 v[118:119], v[38:39], v[38:39]
	s_waitcnt vmcnt(0)
; #define GAS __attribute__((address_space(1)))
; __device__ __forceinline__ v4u pack8(const float (&f)[8]) { v4u w; w.x = pk2(f[0], f[1]); w.y = pk2(f[2], f[3]); w.z = pk2(f[4], f[5]); w.w = pk2(f[6], f[7]); return w; }
; __device__ __forceinline__ float fexp2(float x) { return __builtin_amdgcn_exp2f(x); }
; __device__ __forceinline__ float frcp(float x) { return __builtin_amdgcn_rcpf(x); }
;     __device__ __forceinline__ void operator()(const af4 (&acc)[2][2][4][2], const pg8::Unit& u, int wr_, int wc_, int fr_, int fq_) const {
;     ...
;             for (int m = 0; m < 4; ++m) {
;                 if (ai == 0 && m == 0) load_raw(1);
;                 const int it = wr * 64 + m * 16 + fr;
;                 bf16x8 wf[4];
; #pragma unroll
;                 for (int ks = 0; ks < 4; ++ks) wf[ks] = *(const GAS bf16x8*)(wsg + (size_t)it * 128 + 32 * ks + 8 * fq);
;                 const float bsi = bs[grp * 128 + it];
;                 af4 vm[2] = {(af4){bsi, bsi, bsi, bsi}, (af4){bsi, bsi, bsi, bsi}};
; #pragma unroll
;                 for (int ks = 0; ks < 4; ++ks) {
; #pragma unroll
;                     for (int n = 0; n < 2; ++n) vm[n] = __builtin_amdgcn_mfma_f32_16x16x32_bf16(av[n][ks], wf[ks], vm[n], 0, 0, 0);
;                 }
;                 float o[8];
; #pragma unroll
;                 for (int n = 0; n < 2; ++n)
; #pragma unroll
;                     for (int e = 0; e < 4; e += 2) {
;                         const f32x2 uu = {acc[ai][0][m][n][e], acc[ai][0][m][n][e + 1]}, gg = {acc[ai][1][m][n][e], acc[ai][1][m][n][e + 1]}, vv = {vm[n][e], vm[n][e + 1]};
;                         const f32x2 ar = uu * (uu * uu * (-2.302208198f * 0.044715f) + (-2.302208198f));
;                         const f32x2 gs = gg * (-1.4426950408889634f);
;                         const f32x2 ea = {fexp2(ar.x), fexp2(ar.y)}, eb = {fexp2(gs.x), fexp2(gs.y)};
;                         const f32x2 q = eb + 1.0f, den = ea * q + q;
;                         const f32x2 r = {frcp(den.x), frcp(den.y)};
;                         const f32x2 w = (uu * gg) * vv * r;
;                         o[4 * n + e] = w.x; o[4 * n + e + 1] = w.y; }
;                 *(GAS v4u*)(Y + (size_t)(tok0 + it) * CW + chbase + 32 * wc + 8 * fq) = pack8(o);
	v_mfma_f32_16x16x32_bf16 v[50:53], v[90:93], v[122:125], v[50:53]
	v_mul_f32_e64 v120, v34, s20
	v_mul_f32_e64 v121, v35, s20
	v_pk_fma_f32 v[116:117], v[116:117], s[16:17], v[196:197] op_sel_hi:[1,0,0] neg_lo:[1,0,0] neg_hi:[1,0,0]
	v_pk_mul_f32 v[46:47], v[42:43], v[46:47]
	v_mfma_f32_16x16x32_bf16 v[54:57], v[94:97], v[122:125], v[54:57]
	v_mul_f32_e64 v122, v38, v34
	v_mul_f32_e64 v123, v39, v35
	s_nop 0
	v_pk_mul_f32 v[50:51], v[62:63], v[50:51]
	v_pk_mul_f32 v[52:53], v[64:65], v[52:53]
	v_pk_mul_f32 v[50:51], v[58:59], v[50:51]
	v_pk_mul_f32 v[52:53], v[60:61], v[52:53]
	s_nop 0
	v_pk_mul_f32 v[54:55], v[138:139], v[54:55]
	v_pk_mul_f32 v[56:57], v[140:141], v[56:57]
	v_pk_mul_f32 v[54:55], v[106:107], v[54:55]
	v_pk_mul_f32 v[56:57], v[108:109], v[56:57]
	v_cvt_pk_bf16_f32 v50, v50, v51
	v_cvt_pk_bf16_f32 v51, v52, v53
	v_cvt_pk_bf16_f32 v52, v54, v55
	v_pk_mul_f32 v[34:35], v[36:37], s[20:21] op_sel_hi:[1,0]
	v_cvt_pk_bf16_f32 v53, v56, v57
	global_store_dwordx4 v[110:111], v[50:53], off
	global_load_dword v50, v[200:201], off offset:64
	s_nop 0
	global_load_dwordx4 v[54:57], v[216:217], off
	global_load_dwordx4 v[58:61], v[216:217], off offset:64
	global_load_dwordx4 v[62:65], v[216:217], off offset:128
	global_load_dwordx4 v[106:109], v[216:217], off offset:192
	v_pk_mul_f32 v[52:53], v[44:45], v[44:45]
	v_pk_mul_f32 v[110:111], v[42:43], v[42:43]
	v_pk_mul_f32 v[124:125], v[40:41], v[36:37]
	v_pk_fma_f32 v[36:37], v[110:111], s[16:17], v[196:197] op_sel_hi:[1,0,0] neg_lo:[1,0,0] neg_hi:[1,0,0]
	v_pk_fma_f32 v[52:53], v[52:53], s[16:17], v[196:197] op_sel_hi:[1,0,0] neg_lo:[1,0,0] neg_hi:[1,0,0]
	v_exp_f32_e32 v110, v112
	v_exp_f32_e32 v111, v113
	v_exp_f32_e32 v112, v114
	v_exp_f32_e32 v113, v115
	v_pk_fma_f32 v[114:115], v[118:119], s[16:17], v[196:197] op_sel_hi:[1,0,0] neg_lo:[1,0,0] neg_hi:[1,0,0]
	v_exp_f32_e32 v118, v120
	v_exp_f32_e32 v119, v121
	v_exp_f32_e32 v120, v34
	v_exp_f32_e32 v121, v35
	v_pk_mul_f32 v[34:35], v[42:43], v[36:37]
	v_pk_mul_f32 v[36:37], v[44:45], v[52:53]
	v_pk_mul_f32 v[48:49], v[44:45], v[48:49]
	v_pk_mul_f32 v[38:39], v[38:39], v[114:115]
	v_pk_mul_f32 v[40:41], v[40:41], v[116:117]
	v_exp_f32_e32 v42, v34
	v_exp_f32_e32 v43, v35
	v_exp_f32_e32 v44, v36
	v_exp_f32_e32 v45, v37
	v_exp_f32_e32 v114, v38
	v_exp_f32_e32 v115, v39
	v_exp_f32_e32 v116, v40
	v_exp_f32_e32 v117, v41
	v_pk_add_f32 v[110:111], v[110:111], 1.0 op_sel_hi:[1,0]
	v_pk_add_f32 v[112:113], v[112:113], 1.0 op_sel_hi:[1,0]
	v_pk_add_f32 v[118:119], v[118:119], 1.0 op_sel_hi:[1,0]
	v_pk_add_f32 v[120:121], v[120:121], 1.0 op_sel_hi:[1,0]
	v_pk_fma_f32 v[42:43], v[42:43], v[110:111], v[110:111]
	v_pk_fma_f32 v[44:45], v[44:45], v[112:113], v[112:113]
	v_rcp_f32_e32 v42, v42
	v_rcp_f32_e32 v43, v43
	v_rcp_f32_e32 v44, v44
	v_rcp_f32_e32 v45, v45
	s_waitcnt vmcnt(4)
	v_mov_b32_e32 v51, v50
	v_mov_b32_e32 v52, v50
	v_mov_b32_e32 v53, v50
	s_waitcnt vmcnt(3)
	s_nop 0
	v_mfma_f32_16x16x32_bf16 v[34:37], v[70:73], v[54:57], v[50:53]
	v_mfma_f32_16x16x32_bf16 v[38:41], v[66:69], v[54:57], v[50:53]
	v_add_u32_e32 v54, s23, v212
	v_mad_i64_i32 v[54:55], s[26:27], v54, s61, v[198:199]
	s_waitcnt vmcnt(2)
	v_mfma_f32_16x16x32_bf16 v[34:37], v[78:81], v[58:61], v[34:37]
	v_fma_f32 v50, v114, v118, v118
	v_fma_f32 v51, v115, v119, v119
	v_pk_fma_f32 v[52:53], v[116:117], v[120:121], v[120:121]
	v_rcp_f32_e32 v50, v50
	v_mfma_f32_16x16x32_bf16 v[38:41], v[74:77], v[58:61], v[38:41]
	v_rcp_f32_e32 v51, v51
	v_rcp_f32_e32 v52, v52
	v_rcp_f32_e32 v53, v53
	s_waitcnt vmcnt(1)
	v_mfma_f32_16x16x32_bf16 v[34:37], v[86:89], v[62:65], v[34:37]
	v_lshl_add_u64 v[54:55], v[54:55], 0, s[40:41]
	v_lshl_add_u64 v[54:55], v[54:55], 0, s[6:7]
	v_lshl_add_u64 v[54:55], v[54:55], 0, v[186:187]
	v_mfma_f32_16x16x32_bf16 v[38:41], v[82:85], v[62:65], v[38:41]
	v_mul_f32_e64 v56, v30, s20
	v_mul_f32_e64 v57, v31, s20
	v_pk_mul_f32 v[58:59], v[32:33], s[20:21] op_sel_hi:[1,0]
	v_pk_mul_f32 v[60:61], v[24:25], v[24:25]
	s_waitcnt vmcnt(0)
	v_mfma_f32_16x16x32_bf16 v[34:37], v[90:93], v[106:109], v[34:37]
	v_mul_f32_e64 v62, v22, v22
	v_mul_f32_e64 v63, v23, v23
	v_pk_mul_f32 v[64:65], v[18:19], s[20:21] op_sel_hi:[1,0]
	v_pk_fma_f32 v[60:61], v[60:61], s[16:17], v[196:197] op_sel_hi:[1,0,0] neg_lo:[1,0,0] neg_hi:[1,0,0]
	v_mfma_f32_16x16x32_bf16 v[38:41], v[94:97], v[106:109], v[38:41]
	v_mul_f32_e64 v106, v24, v20
	v_mul_f32_e64 v107, v25, v21
	s_nop 0
	v_pk_mul_f32 v[34:35], v[46:47], v[34:35]
	v_pk_mul_f32 v[36:37], v[48:49], v[36:37]
	v_pk_mul_f32 v[34:35], v[42:43], v[34:35]
	v_pk_mul_f32 v[36:37], v[44:45], v[36:37]
	s_nop 0
	v_pk_mul_f32 v[38:39], v[122:123], v[38:39]
	v_pk_mul_f32 v[40:41], v[124:125], v[40:41]
	v_pk_mul_f32 v[38:39], v[50:51], v[38:39]
	v_pk_mul_f32 v[40:41], v[52:53], v[40:41]
	v_cvt_pk_bf16_f32 v34, v34, v35
	v_cvt_pk_bf16_f32 v35, v36, v37
	v_cvt_pk_bf16_f32 v36, v38, v39
	v_pk_mul_f32 v[30:31], v[26:27], v[30:31]
	v_cvt_pk_bf16_f32 v37, v40, v41
	global_store_dwordx4 v[54:55], v[34:37], off
	global_load_dword v34, v[200:201], off offset:128
	s_nop 0
	global_load_dwordx4 v[38:41], v[102:103], off
	global_load_dwordx4 v[42:45], v[102:103], off offset:64
	global_load_dwordx4 v[46:49], v[102:103], off offset:128
	global_load_dwordx4 v[50:53], v[102:103], off offset:192
	v_pk_mul_f32 v[36:37], v[28:29], v[28:29]
	v_pk_mul_f32 v[54:55], v[26:27], v[26:27]
	v_pk_mul_f32 v[102:103], v[22:23], v[18:19]
	v_pk_mul_f32 v[18:19], v[20:21], s[20:21] op_sel_hi:[1,0]
	v_pk_fma_f32 v[20:21], v[54:55], s[16:17], v[196:197] op_sel_hi:[1,0,0] neg_lo:[1,0,0] neg_hi:[1,0,0]
	v_pk_fma_f32 v[36:37], v[36:37], s[16:17], v[196:197] op_sel_hi:[1,0,0] neg_lo:[1,0,0] neg_hi:[1,0,0]
	v_exp_f32_e32 v54, v56
	v_exp_f32_e32 v55, v57
	v_exp_f32_e32 v56, v58
	v_exp_f32_e32 v57, v59
	v_pk_fma_f32 v[58:59], v[62:63], s[16:17], v[196:197] op_sel_hi:[1,0,0] neg_lo:[1,0,0] neg_hi:[1,0,0]
	v_exp_f32_e32 v62, v64
	v_exp_f32_e32 v63, v65
	v_exp_f32_e32 v64, v18
	v_exp_f32_e32 v65, v19
	v_pk_mul_f32 v[18:19], v[26:27], v[20:21]
	v_pk_mul_f32 v[20:21], v[28:29], v[36:37]
	v_pk_mul_f32 v[32:33], v[28:29], v[32:33]
	v_pk_mul_f32 v[22:23], v[22:23], v[58:59]
	v_pk_mul_f32 v[24:25], v[24:25], v[60:61]
	v_exp_f32_e32 v26, v18
	v_exp_f32_e32 v27, v19
	v_exp_f32_e32 v28, v20
	v_exp_f32_e32 v29, v21
	v_exp_f32_e32 v58, v22
	v_exp_f32_e32 v59, v23
	v_exp_f32_e32 v60, v24
	v_exp_f32_e32 v61, v25
	v_pk_add_f32 v[54:55], v[54:55], 1.0 op_sel_hi:[1,0]
	v_pk_add_f32 v[56:57], v[56:57], 1.0 op_sel_hi:[1,0]
	v_pk_add_f32 v[62:63], v[62:63], 1.0 op_sel_hi:[1,0]
	v_pk_add_f32 v[64:65], v[64:65], 1.0 op_sel_hi:[1,0]
	v_pk_fma_f32 v[26:27], v[26:27], v[54:55], v[54:55]
	v_pk_fma_f32 v[28:29], v[28:29], v[56:57], v[56:57]
	v_rcp_f32_e32 v26, v26
	v_rcp_f32_e32 v27, v27
	v_rcp_f32_e32 v28, v28
	v_rcp_f32_e32 v29, v29
	s_waitcnt vmcnt(4)
; template <class Epi, class Sched, bool ALIGN_EPI = false, bool SP2 = false>
; __device__ __forceinline__ void gemm_phase(PG8_LAS unsigned char* lds, const Gemm g, const Sched& S, const Epi& E) {
;     ...
;         if (!has_next) break;
; #pragma unroll
;         for (int a = 0; a < 2; ++a)
; #pragma unroll
;             for (int b = 0; b < 2; ++b)
; #pragma unroll
;                 for (int m = 0; m < 4; ++m)
; #pragma unroll
;                     for (int n = 0; n < 2; ++n) acc[a][b][m][n] = (f32x4){0.f, 0.f, 0.f, 0.f};
;     __device__ __forceinline__ void operator()(const af4 (&acc)[2][2][4][2], const pg8::Unit& u, int wr_, int wc_, int fr_, int fq_) const {
;     ...
;             for (int m = 0; m < 4; ++m) {
;                 if (ai == 0 && m == 0) load_raw(1);
;                 const int it = wr * 64 + m * 16 + fr;
;                 bf16x8 wf[4];
; #pragma unroll
;                 for (int ks = 0; ks < 4; ++ks) wf[ks] = *(const GAS bf16x8*)(wsg + (size_t)it * 128 + 32 * ks + 8 * fq);
;                 const float bsi = bs[grp * 128 + it];
;                 af4 vm[2] = {(af4){bsi, bsi, bsi, bsi}, (af4){bsi, bsi, bsi, bsi}};
; #pragma unroll
;                 for (int ks = 0; ks < 4; ++ks) {
; #pragma unroll
;                     for (int n = 0; n < 2; ++n) vm[n] = __builtin_amdgcn_mfma_f32_16x16x32_bf16(av[n][ks], wf[ks], vm[n], 0, 0, 0);
;                 }
;                 float o[8];
; #pragma unroll
;                 for (int n = 0; n < 2; ++n)
; #pragma unroll
;                     for (int e = 0; e < 4; e += 2) {
;                         const f32x2 uu = {acc[ai][0][m][n][e], acc[ai][0][m][n][e + 1]}, gg = {acc[ai][1][m][n][e], acc[ai][1][m][n][e + 1]}, vv = {vm[n][e], vm[n][e + 1]};
;                         const f32x2 ar = uu * (uu * uu * (-2.302208198f * 0.044715f) + (-2.302208198f));
;                         const f32x2 gs = gg * (-1.4426950408889634f);
;                         const f32x2 ea = {fexp2(ar.x), fexp2(ar.y)}, eb = {fexp2(gs.x), fexp2(gs.y)};
;                         const f32x2 q = eb + 1.0f, den = ea * q + q;
;                         const f32x2 r = {frcp(den.x), frcp(den.y)};
;                         const f32x2 w = (uu * gg) * vv * r;
;                         o[4 * n + e] = w.x; o[4 * n + e + 1] = w.y; }
;                 *(GAS v4u*)(Y + (size_t)(tok0 + it) * CW + chbase + 32 * wc + 8 * fq) = pack8(o);
	v_mov_b32_e32 v35, v34
	v_mov_b32_e32 v36, v34
	v_mov_b32_e32 v37, v34
	s_waitcnt vmcnt(3)
	s_nop 0
	v_mfma_f32_16x16x32_bf16 v[18:21], v[70:73], v[38:41], v[34:37]
	v_mfma_f32_16x16x32_bf16 v[22:25], v[66:69], v[38:41], v[34:37]
	v_add_u32_e32 v38, s23, v98
	v_mad_i64_i32 v[38:39], s[26:27], v38, s61, v[198:199]
	s_waitcnt vmcnt(2)
	v_mfma_f32_16x16x32_bf16 v[18:21], v[78:81], v[42:45], v[18:21]
	v_fma_f32 v34, v58, v62, v62
	v_fma_f32 v35, v59, v63, v63
	v_pk_fma_f32 v[36:37], v[60:61], v[64:65], v[64:65]
	v_rcp_f32_e32 v34, v34
	v_mfma_f32_16x16x32_bf16 v[22:25], v[74:77], v[42:45], v[22:25]
	v_rcp_f32_e32 v35, v35
	v_rcp_f32_e32 v36, v36
	v_rcp_f32_e32 v37, v37
	s_waitcnt vmcnt(1)
	v_mfma_f32_16x16x32_bf16 v[18:21], v[86:89], v[46:49], v[18:21]
	v_lshl_add_u64 v[38:39], v[38:39], 0, s[40:41]
	v_lshl_add_u64 v[38:39], v[38:39], 0, s[6:7]
	v_lshl_add_u64 v[38:39], v[38:39], 0, v[186:187]
	v_mfma_f32_16x16x32_bf16 v[22:25], v[82:85], v[46:49], v[22:25]
	v_mul_f32_e64 v40, v14, s20
	v_mul_f32_e64 v41, v15, s20
	v_pk_mul_f32 v[42:43], v[16:17], s[20:21] op_sel_hi:[1,0]
	v_pk_mul_f32 v[44:45], v[8:9], v[8:9]
	s_waitcnt vmcnt(0)
	v_mfma_f32_16x16x32_bf16 v[18:21], v[90:93], v[50:53], v[18:21]
	v_mul_f32_e64 v46, v6, v6
	v_mul_f32_e64 v47, v7, v7
	v_pk_mul_f32 v[48:49], v[2:3], s[20:21] op_sel_hi:[1,0]
	v_pk_fma_f32 v[44:45], v[44:45], s[16:17], v[196:197] op_sel_hi:[1,0,0] neg_lo:[1,0,0] neg_hi:[1,0,0]
	v_mfma_f32_16x16x32_bf16 v[22:25], v[94:97], v[50:53], v[22:25]
	v_mul_f32_e64 v50, v6, v2
	v_mul_f32_e64 v51, v7, v3
	s_nop 0
	v_pk_mul_f32 v[18:19], v[30:31], v[18:19]
	v_pk_mul_f32 v[20:21], v[32:33], v[20:21]
	v_pk_mul_f32 v[18:19], v[26:27], v[18:19]
	v_pk_mul_f32 v[20:21], v[28:29], v[20:21]
	s_nop 0
	v_pk_mul_f32 v[22:23], v[102:103], v[22:23]
	v_pk_mul_f32 v[24:25], v[106:107], v[24:25]
	v_pk_mul_f32 v[22:23], v[34:35], v[22:23]
	v_pk_mul_f32 v[24:25], v[36:37], v[24:25]
	v_cvt_pk_bf16_f32 v18, v18, v19
	v_cvt_pk_bf16_f32 v19, v20, v21
	v_cvt_pk_bf16_f32 v20, v22, v23
	v_pk_mul_f32 v[2:3], v[4:5], s[20:21] op_sel_hi:[1,0]
	v_cvt_pk_bf16_f32 v21, v24, v25
	global_store_dwordx4 v[38:39], v[18:21], off
	global_load_dword v18, v[200:201], off offset:192
	s_nop 0
	global_load_dwordx4 v[22:25], v[104:105], off
	global_load_dwordx4 v[26:29], v[104:105], off offset:64
	global_load_dwordx4 v[30:33], v[104:105], off offset:128
	global_load_dwordx4 v[34:37], v[104:105], off offset:192
	v_pk_mul_f32 v[20:21], v[12:13], v[12:13]
	v_pk_mul_f32 v[38:39], v[10:11], v[10:11]
	v_pk_mul_f32 v[52:53], v[8:9], v[4:5]
	v_pk_fma_f32 v[4:5], v[38:39], s[16:17], v[196:197] op_sel_hi:[1,0,0] neg_lo:[1,0,0] neg_hi:[1,0,0]
	v_pk_fma_f32 v[20:21], v[20:21], s[16:17], v[196:197] op_sel_hi:[1,0,0] neg_lo:[1,0,0] neg_hi:[1,0,0]
	v_exp_f32_e32 v38, v40
	v_exp_f32_e32 v39, v41
	v_exp_f32_e32 v40, v42
	v_exp_f32_e32 v41, v43
	v_pk_fma_f32 v[42:43], v[46:47], s[16:17], v[196:197] op_sel_hi:[1,0,0] neg_lo:[1,0,0] neg_hi:[1,0,0]
	v_exp_f32_e32 v46, v48
	v_exp_f32_e32 v47, v49
	v_exp_f32_e32 v48, v2
	v_exp_f32_e32 v49, v3
	v_pk_mul_f32 v[2:3], v[10:11], v[4:5]
	v_pk_mul_f32 v[4:5], v[12:13], v[20:21]
	v_pk_mul_f32 v[14:15], v[10:11], v[14:15]
	v_pk_mul_f32 v[16:17], v[12:13], v[16:17]
	v_pk_mul_f32 v[6:7], v[6:7], v[42:43]
	v_pk_mul_f32 v[8:9], v[8:9], v[44:45]
	v_exp_f32_e32 v10, v2
	v_exp_f32_e32 v11, v3
	v_exp_f32_e32 v12, v4
	v_exp_f32_e32 v13, v5
	v_exp_f32_e32 v42, v6
	v_exp_f32_e32 v43, v7
	v_exp_f32_e32 v44, v8
	v_exp_f32_e32 v45, v9
	v_pk_add_f32 v[38:39], v[38:39], 1.0 op_sel_hi:[1,0]
	v_pk_add_f32 v[40:41], v[40:41], 1.0 op_sel_hi:[1,0]
	v_pk_add_f32 v[46:47], v[46:47], 1.0 op_sel_hi:[1,0]
	v_pk_add_f32 v[48:49], v[48:49], 1.0 op_sel_hi:[1,0]
	v_pk_fma_f32 v[10:11], v[10:11], v[38:39], v[38:39]
	v_pk_fma_f32 v[12:13], v[12:13], v[40:41], v[40:41]
	v_rcp_f32_e32 v10, v10
	v_rcp_f32_e32 v11, v11
	v_rcp_f32_e32 v12, v12
	v_rcp_f32_e32 v13, v13
	s_waitcnt vmcnt(4)
	v_mov_b32_e32 v19, v18
	v_mov_b32_e32 v20, v18
	v_mov_b32_e32 v21, v18
	s_waitcnt vmcnt(3)
	s_nop 0
	v_mfma_f32_16x16x32_bf16 v[2:5], v[70:73], v[22:25], v[18:21]
	v_mfma_f32_16x16x32_bf16 v[6:9], v[66:69], v[22:25], v[18:21]
	v_add_u32_e32 v22, s23, v100
	v_mad_i64_i32 v[22:23], s[4:5], v22, s61, v[198:199]
	s_waitcnt vmcnt(2)
	v_mfma_f32_16x16x32_bf16 v[2:5], v[78:81], v[26:29], v[2:5]
	v_fma_f32 v18, v42, v46, v46
	v_fma_f32 v19, v43, v47, v47
	v_pk_fma_f32 v[20:21], v[44:45], v[48:49], v[48:49]
	v_rcp_f32_e32 v18, v18
	v_mfma_f32_16x16x32_bf16 v[6:9], v[74:77], v[26:29], v[6:9]
	v_rcp_f32_e32 v19, v19
	v_rcp_f32_e32 v20, v20
	v_rcp_f32_e32 v21, v21
	s_waitcnt vmcnt(1)
	v_mfma_f32_16x16x32_bf16 v[2:5], v[86:89], v[30:33], v[2:5]
	v_lshl_add_u64 v[22:23], v[22:23], 0, s[40:41]
	v_lshl_add_u64 v[22:23], v[22:23], 0, s[6:7]
	v_lshl_add_u64 v[22:23], v[22:23], 0, v[186:187]
	v_mfma_f32_16x16x32_bf16 v[6:9], v[82:85], v[30:33], v[6:9]
	s_mov_b64 s[4:5], -1
	s_waitcnt vmcnt(0)
	v_mfma_f32_16x16x32_bf16 v[2:5], v[90:93], v[34:37], v[2:5]
	v_mfma_f32_16x16x32_bf16 v[6:9], v[94:97], v[34:37], v[6:9]
	s_nop 6
	v_mul_f32_e64 v2, v14, v2
	v_mul_f32_e64 v3, v15, v3
	v_pk_mul_f32 v[4:5], v[16:17], v[4:5]
	v_pk_mul_f32 v[6:7], v[50:51], v[6:7]
	v_pk_mul_f32 v[8:9], v[52:53], v[8:9]
	v_pk_mul_f32 v[2:3], v[10:11], v[2:3]
	v_pk_mul_f32 v[4:5], v[12:13], v[4:5]
	v_pk_mul_f32 v[6:7], v[18:19], v[6:7]
	v_pk_mul_f32 v[8:9], v[20:21], v[8:9]
	v_cvt_pk_bf16_f32 v2, v2, v3
	v_cvt_pk_bf16_f32 v3, v4, v5
	v_cvt_pk_bf16_f32 v4, v6, v7
	s_nop 0
	v_cvt_pk_bf16_f32 v5, v8, v9
	global_store_dwordx4 v[22:23], v[2:5], off
	s_cbranch_vccnz .LBB0_1123
	s_andn2_b64 vcc, exec, s[10:11]
	s_cbranch_vccnz .LBB0_1122
	s_barrier
	s_branch .LBB0_1122
